# attention queues: next ticket requested during the last key tile of the current unit (epilogue start for the neighbourhood kind), loop top only publishes it
# baseline (speedup 1.0000x reference)
; template <int Q>
; DI void attn_queue(const Params& p, int l, char* smem, int* s_unit, int cb) {
;     const bool ctxu = l < DEPTH - 1;
;     const int total = (Q == 0) ? (ctxu ? 576 : 512) : (Q == 1) ? (ctxu ? 960 : 768) : 768;
;     for (;;) {
;         if (threadIdx.x == 0) *s_unit = (int)atomicAdd(p.ctr + cb + l * 4 + Q, 1u);
;         __syncthreads();
;         const int u = *s_unit;
;         __syncthreads();
;         if (u >= total) break;
.LBB0_69:
	s_andn2_b64 vcc, exec, s[4:5]
	s_cbranch_vccnz .LBB0_136
	s_cmp_lt_i32 s60, 3
	s_cselect_b64 s[44:45], -1, 0
	s_and_b64 s[4:5], s[44:45], exec
	s_movk_i32 s4, 0x240
	s_cselect_b32 s28, s4, 0x200
	s_lshl_b32 s4, s60, 6
	s_and_b32 s48, s99, -4
	s_ashr_i32 s5, s4, 31
	s_ashr_i32 s49, s48, 31
	s_ashr_i32 s61, s60, 31
	s_lshl_b64 s[46:47], s[4:5], 2
	s_and_saveexec_b64 s[4:5], s[54:55]
	s_cbranch_execz .Ltk_e0
	s_load_dwordx2 s[100:101], s[0:1], 0x100
	s_lshl_b32 m0, s48, 2
	v_mov_b32_e32 v253, 1
	s_waitcnt lgkmcnt(0)
	s_add_u32 s100, s100, m0
	s_addc_u32 s101, s101, 0
	global_atomic_add v253, v193, v253, s[100:101] sc0
.Ltk_e0:
	s_or_b64 exec, exec, s[4:5]
	s_branch .LBB0_72

; template <int Q>
; DI void attn_queue(const Params& p, int l, char* smem, int* s_unit, int cb) {
;     ...
;     for (;;) {
;         if (threadIdx.x == 0) *s_unit = (int)atomicAdd(p.ctr + cb + l * 4 + Q, 1u);
;         __syncthreads();
;         const int u = *s_unit;
;         __syncthreads();
.LBB0_72:
	s_and_saveexec_b64 s[4:5], s[54:55]
	s_cbranch_execz .LBB0_76
	s_waitcnt vmcnt(0)
	ds_write_b32 v193, v253 offset:16

; #define MFMA(a, b, c) __builtin_amdgcn_mfma_f32_32x32x16_bf16((a), (b), (c), 0, 0, 0)
; #define KV_ISSUE(tile_, slot_) do { \
;     const bf16_t* kp_ = kbase + (size_t)(tile_) * 4096 + kvoff; const bf16_t* vp_ = vbase + (size_t)(tile_) * 4096 + kvoff; \
;     char* lp_ = smem + (slot_) * ATT_SLOT + tid * 16; \
;     dma16(kp_, lp_); dma16(kp_ + 2048, lp_ + 4096); dma16(vp_, lp_ + ATT_V); dma16(vp_ + 2048, lp_ + ATT_V + 4096); } while (0)
; template <int KIND>
; DI void attn_unit(const Params& p, int l, int b, int head, int qt, int qcol, int kcol, int vfeat, int gcol, int mixcol,
;                   int t1, int n1, int t2, int n2, char* smem) {
;     ...
;     for (int it = 0; it < nt; ++it) {
;         const int tile = (it < n1) ? t1 + it : t2 + (it - n1);
;         if (it + 1 < nt) asm volatile("s_waitcnt vmcnt(4)" ::: "memory"); else asm volatile("s_waitcnt vmcnt(0)" ::: "memory");
;         __builtin_amdgcn_s_barrier();
;         const char* sk = smem + sc * ATT_SLOT;
;         const char* sv = sk + ATT_V;
;         bool active = true;
;         if (KIND == 2 && tile < 32) active = (tile >= r0w) && (tile < r0w + 8);
;         bf16x8 kf[8], vf[8];
;         if (active) {
; #pragma unroll
;             for (int s = 0; s < 4; ++s)
; #pragma unroll
;                 for (int t = 0; t < 2; ++t) kf[2 * s + t] = *(const bf16x8*)(sk + (32 * t + r) * 128 + (((2 * s + h) ^ xr) << 4));
;         }
;         __builtin_amdgcn_sched_barrier(0);
;         if (it + 2 < nt) { const int nx = (it + 2 < n1) ? t1 + it + 2 : t2 + (it + 2 - n1); KV_ISSUE(nx, sn); }
;         sc = (sc == 2) ? 0 : sc + 1; sn = (sn == 2) ? 0 : sn + 1;
;         __builtin_amdgcn_sched_barrier(0);
;         if (active) {
;     ...
;             if (KIND == 0) {
;                 f32x16 S0[2], S1[2];
; #pragma unroll
;                 for (int t = 0; t < 2; ++t) { S0[t] = MFMA(kf[t], qf[0], cz); S1[t] = MFMA(kf[4 + t], qf[2], cz); }
; #pragma unroll
;                 for (int t = 0; t < 2; ++t) { S0[t] = MFMA(kf[2 + t], qf[1], S0[t]); S1[t] = MFMA(kf[6 + t], qf[3], S1[t]); }
;                 LOAD_VF();
;                 softmax_tile(S0, l0);
;                 pv_tile(S0, O0, vf);
;                 softmax_tile(S1, l1);
;                 pv_tile(S1, O1, vf);
.LBB0_82:
	v_lshl_add_u32 v225, s35, 14, v221
	v_add_u32_e32 v222, v225, v218
	v_add_u32_e32 v223, v225, v216
	v_add_u32_e32 v224, v225, v215
	v_add_u32_e32 v225, v225, v219
	s_waitcnt vmcnt(4)
	s_barrier
	ds_read_b128 v[234:237], v225
	ds_read_b128 v[238:241], v225 offset:4096
	ds_read_b128 v[242:245], v222
	ds_read_b128 v[246:249], v222 offset:4096
	v_lshl_add_u64 v[226:227], v[198:199], 0, s[4:5]
	s_mov_b64 s[42:43], 0x904000
	v_lshl_add_u64 v[228:229], v[226:227], 0, s[42:43]
	s_mov_b64 s[42:43], 0x905000
	v_lshl_add_u64 v[226:227], v[226:227], 0, s[42:43]
	v_lshl_add_u64 v[230:231], v[196:197], 0, s[4:5]
	v_lshl_add_u64 v[232:233], v[230:231], 0, s[92:93]
	v_lshl_add_u64 v[230:231], v[230:231], 0, s[94:95]
	s_lshl_b32 s101, s34, 14
	s_add_i32 s101, s101, s100
	s_add_i32 s42, s35, 1
	s_cmp_lg_u32 s35, 2
	s_cselect_b32 s35, s42, 0
	s_add_i32 s42, s34, 1
	v_add_f32_e32 v252, v80, v252
	v_add_f32_e32 v253, v81, v253
	v_cvt_pk_bf16_f32 v80, v80, v81
	v_add_f32_e32 v252, v82, v252
	v_add_f32_e32 v253, v83, v253
	v_cvt_pk_bf16_f32 v81, v82, v83
	v_add_f32_e32 v252, v84, v252
	v_add_f32_e32 v253, v85, v253
	v_cvt_pk_bf16_f32 v82, v84, v85
	v_add_f32_e32 v252, v86, v252
	v_add_f32_e32 v253, v87, v253
	v_cvt_pk_bf16_f32 v83, v86, v87
	s_mov_b32 m0, s101
	s_waitcnt lgkmcnt(0)
	v_mfma_f32_32x32x16_bf16 v[128:143], v[234:237], v[152:155], v[0:15]
	global_load_lds_dwordx4 v[228:229], off
	s_add_u32 m0, s101, 0x1000
	v_add_f32_e32 v252, v88, v252
	v_add_f32_e32 v253, v89, v253
	v_cvt_pk_bf16_f32 v88, v88, v89
	v_mfma_f32_32x32x16_bf16 v[112:127], v[238:241], v[152:155], v[0:15]
	global_load_lds_dwordx4 v[226:227], off
	s_add_u32 m0, s101, 0x2000
	v_add_f32_e32 v252, v90, v252
	v_add_f32_e32 v253, v91, v253
	v_cvt_pk_bf16_f32 v89, v90, v91
	v_mfma_f32_32x32x16_bf16 v[128:143], v[242:245], v[144:147], v[128:143]
	global_load_lds_dwordx4 v[232:233], off
	s_add_u32 m0, s101, 0x3000
	v_add_f32_e32 v252, v92, v252
	v_add_f32_e32 v253, v93, v253
	v_cvt_pk_bf16_f32 v90, v92, v93
	v_mfma_f32_32x32x16_bf16 v[112:127], v[246:249], v[144:147], v[112:127]
	global_load_lds_dwordx4 v[230:231], off
	v_add_f32_e32 v252, v94, v252
	v_add_f32_e32 v253, v95, v253
	v_cvt_pk_bf16_f32 v91, v94, v95
	v_add_f32_e32 v252, v252, v253
	v_add_f32_e32 v194, v194, v252
	s_cmp_lg_u32 s34, 2
	s_cselect_b32 s34, s42, 0
	ds_read_b128 v[234:237], v223
	ds_read_b128 v[238:241], v223 offset:4096
	ds_read_b128 v[242:245], v224
	ds_read_b128 v[246:249], v224 offset:4096
	v_mfma_f32_32x32x16_bf16 v[64:79], v[188:191], v[96:99], v[64:79]
	v_exp_f32_e32 v128, v128
	v_exp_f32_e32 v129, v129
	v_exp_f32_e32 v130, v130
	v_exp_f32_e32 v131, v131
	v_mfma_f32_32x32x16_bf16 v[16:31], v[184:187], v[96:99], v[16:31]
	v_exp_f32_e32 v132, v132
	v_exp_f32_e32 v133, v133
	v_exp_f32_e32 v134, v134
	v_exp_f32_e32 v135, v135
	v_mfma_f32_32x32x16_bf16 v[64:79], v[180:183], v[104:107], v[64:79]
	v_exp_f32_e32 v136, v136
	v_exp_f32_e32 v137, v137
	v_exp_f32_e32 v138, v138
	v_exp_f32_e32 v139, v139
	v_add_f32_e64 v250, v128, 0
	v_add_f32_e64 v251, v129, 0
	v_cvt_pk_bf16_f32 v128, v128, v129
	v_add_f32_e32 v250, v130, v250
	v_add_f32_e32 v251, v131, v251
	v_cvt_pk_bf16_f32 v129, v130, v131
	v_mfma_f32_32x32x16_bf16 v[16:31], v[176:179], v[104:107], v[16:31]
	v_exp_f32_e32 v140, v140
	v_exp_f32_e32 v141, v141
	v_exp_f32_e32 v142, v142
	v_exp_f32_e32 v143, v143
	v_add_f32_e32 v250, v132, v250
	v_add_f32_e32 v251, v133, v251
	v_cvt_pk_bf16_f32 v130, v132, v133
	v_add_f32_e32 v250, v134, v250
	v_add_f32_e32 v251, v135, v251
	v_cvt_pk_bf16_f32 v131, v134, v135
	v_mfma_f32_32x32x16_bf16 v[64:79], v[172:175], v[80:83], v[64:79]
	v_exp_f32_e32 v112, v112
	v_exp_f32_e32 v113, v113
	v_exp_f32_e32 v114, v114
	v_exp_f32_e32 v115, v115
	v_add_f32_e32 v250, v136, v250
	v_add_f32_e32 v251, v137, v251
	v_cvt_pk_bf16_f32 v136, v136, v137
	v_add_f32_e32 v250, v138, v250
	v_add_f32_e32 v251, v139, v251
	v_cvt_pk_bf16_f32 v137, v138, v139
	v_mfma_f32_32x32x16_bf16 v[16:31], v[168:171], v[80:83], v[16:31]
	v_exp_f32_e32 v116, v116
	v_exp_f32_e32 v117, v117
	v_exp_f32_e32 v118, v118
	v_exp_f32_e32 v119, v119
	v_add_f32_e32 v250, v140, v250
	v_add_f32_e32 v251, v141, v251
	v_cvt_pk_bf16_f32 v138, v140, v141
	v_add_f32_e32 v250, v142, v250
	v_add_f32_e32 v251, v143, v251
	v_cvt_pk_bf16_f32 v139, v142, v143
	v_mfma_f32_32x32x16_bf16 v[64:79], v[164:167], v[88:91], v[64:79]
	v_exp_f32_e32 v120, v120
	v_exp_f32_e32 v121, v121
	v_exp_f32_e32 v122, v122
	v_exp_f32_e32 v123, v123
	v_mfma_f32_32x32x16_bf16 v[16:31], v[160:163], v[88:91], v[16:31]
	v_exp_f32_e32 v124, v124
	v_exp_f32_e32 v125, v125
	v_exp_f32_e32 v126, v126
	v_exp_f32_e32 v127, v127
	s_waitcnt lgkmcnt(0)
	ds_read_b128 v[188:191], v225 offset:8192
	ds_read_b128 v[184:187], v225 offset:12288
	ds_read_b128 v[180:183], v222 offset:8192
	ds_read_b128 v[176:179], v222 offset:12288
	ds_read_b128 v[172:175], v223 offset:8192
	ds_read_b128 v[168:171], v223 offset:12288
	ds_read_b128 v[164:167], v224 offset:8192
	ds_read_b128 v[160:163], v224 offset:12288
	v_mfma_f32_32x32x16_bf16 v[96:111], v[234:237], v[156:159], v[0:15]
	v_add_f32_e32 v250, v112, v250
	v_add_f32_e32 v251, v113, v251
	v_cvt_pk_bf16_f32 v112, v112, v113
	v_add_f32_e32 v250, v114, v250
	v_add_f32_e32 v251, v115, v251
	v_cvt_pk_bf16_f32 v113, v114, v115
	v_mfma_f32_32x32x16_bf16 v[80:95], v[238:241], v[156:159], v[0:15]
	v_add_f32_e32 v250, v116, v250
	v_add_f32_e32 v251, v117, v251
	v_cvt_pk_bf16_f32 v114, v116, v117
	v_add_f32_e32 v250, v118, v250
	v_add_f32_e32 v251, v119, v251
	v_cvt_pk_bf16_f32 v115, v118, v119
	v_mfma_f32_32x32x16_bf16 v[96:111], v[242:245], v[148:151], v[96:111]
	v_add_f32_e32 v250, v120, v250
	v_add_f32_e32 v251, v121, v251
	v_cvt_pk_bf16_f32 v120, v120, v121
	v_add_f32_e32 v250, v122, v250
	v_add_f32_e32 v251, v123, v251
	v_cvt_pk_bf16_f32 v121, v122, v123
	v_mfma_f32_32x32x16_bf16 v[80:95], v[246:249], v[148:151], v[80:95]
	v_add_f32_e32 v250, v124, v250
	v_add_f32_e32 v251, v125, v251
	v_cvt_pk_bf16_f32 v122, v124, v125
	v_add_f32_e32 v250, v126, v250
	v_add_f32_e32 v251, v127, v251
	v_cvt_pk_bf16_f32 v123, v126, v127
	v_add_f32_e32 v250, v250, v251
	v_add_f32_e32 v195, v195, v250
	s_add_u32 s4, s4, 0x2000
	s_addc_u32 s5, s5, 0
	s_waitcnt lgkmcnt(0)
; #define MFMA(a, b, c) __builtin_amdgcn_mfma_f32_32x32x16_bf16((a), (b), (c), 0, 0, 0)
; #define KV_ISSUE(tile_, slot_) do { \
;     const bf16_t* kp_ = kbase + (size_t)(tile_) * 4096 + kvoff; const bf16_t* vp_ = vbase + (size_t)(tile_) * 4096 + kvoff; \
;     char* lp_ = smem + (slot_) * ATT_SLOT + tid * 16; \
;     dma16(kp_, lp_); dma16(kp_ + 2048, lp_ + 4096); dma16(vp_, lp_ + ATT_V); dma16(vp_ + 2048, lp_ + ATT_V + 4096); } while (0)
; template <int KIND>
; DI void attn_unit(const Params& p, int l, int b, int head, int qt, int qcol, int kcol, int vfeat, int gcol, int mixcol,
;                   int t1, int n1, int t2, int n2, char* smem) {
;     ...
;     for (int it = 0; it < nt; ++it) {
;         const int tile = (it < n1) ? t1 + it : t2 + (it - n1);
;         if (it + 1 < nt) asm volatile("s_waitcnt vmcnt(4)" ::: "memory"); else asm volatile("s_waitcnt vmcnt(0)" ::: "memory");
;         __builtin_amdgcn_s_barrier();
;         const char* sk = smem + sc * ATT_SLOT;
;         const char* sv = sk + ATT_V;
;         bool active = true;
;         if (KIND == 2 && tile < 32) active = (tile >= r0w) && (tile < r0w + 8);
;         bf16x8 kf[8], vf[8];
;         if (active) {
; #pragma unroll
;             for (int s = 0; s < 4; ++s)
; #pragma unroll
;                 for (int t = 0; t < 2; ++t) kf[2 * s + t] = *(const bf16x8*)(sk + (32 * t + r) * 128 + (((2 * s + h) ^ xr) << 4));
;         }
;         __builtin_amdgcn_sched_barrier(0);
;         if (it + 2 < nt) { const int nx = (it + 2 < n1) ? t1 + it + 2 : t2 + (it + 2 - n1); KV_ISSUE(nx, sn); }
;         sc = (sc == 2) ? 0 : sc + 1; sn = (sn == 2) ? 0 : sn + 1;
;         __builtin_amdgcn_sched_barrier(0);
;         if (active) {
;     ...
;             if (KIND == 0) {
;                 f32x16 S0[2], S1[2];
; #pragma unroll
;                 for (int t = 0; t < 2; ++t) { S0[t] = MFMA(kf[t], qf[0], cz); S1[t] = MFMA(kf[4 + t], qf[2], cz); }
; #pragma unroll
;                 for (int t = 0; t < 2; ++t) { S0[t] = MFMA(kf[2 + t], qf[1], S0[t]); S1[t] = MFMA(kf[6 + t], qf[3], S1[t]); }
;                 LOAD_VF();
;                 softmax_tile(S0, l0);
;                 pv_tile(S0, O0, vf);
;                 softmax_tile(S1, l1);
;                 pv_tile(S1, O1, vf);
	v_mfma_f32_32x32x16_bf16 v[48:63], v[188:191], v[128:131], v[48:63]
	v_exp_f32_e32 v96, v96
	v_exp_f32_e32 v97, v97
	v_exp_f32_e32 v98, v98
	v_exp_f32_e32 v99, v99
	v_mfma_f32_32x32x16_bf16 v[32:47], v[184:187], v[128:131], v[32:47]
	v_exp_f32_e32 v100, v100
	v_exp_f32_e32 v101, v101
	v_exp_f32_e32 v102, v102
	v_exp_f32_e32 v103, v103
	v_mfma_f32_32x32x16_bf16 v[48:63], v[180:183], v[136:139], v[48:63]
	v_exp_f32_e32 v104, v104
	v_exp_f32_e32 v105, v105
	v_exp_f32_e32 v106, v106
	v_exp_f32_e32 v107, v107
	v_add_f32_e64 v252, v96, 0
	v_add_f32_e64 v253, v97, 0
	v_cvt_pk_bf16_f32 v96, v96, v97
	v_add_f32_e32 v252, v98, v252
	v_add_f32_e32 v253, v99, v253
	v_cvt_pk_bf16_f32 v97, v98, v99
	v_mfma_f32_32x32x16_bf16 v[32:47], v[176:179], v[136:139], v[32:47]
	v_exp_f32_e32 v108, v108
	v_exp_f32_e32 v109, v109
	v_exp_f32_e32 v110, v110
	v_exp_f32_e32 v111, v111
	v_add_f32_e32 v252, v100, v252
	v_add_f32_e32 v253, v101, v253
	v_cvt_pk_bf16_f32 v98, v100, v101
	v_add_f32_e32 v252, v102, v252
	v_add_f32_e32 v253, v103, v253
	v_cvt_pk_bf16_f32 v99, v102, v103
	v_mfma_f32_32x32x16_bf16 v[48:63], v[172:175], v[112:115], v[48:63]
	v_exp_f32_e32 v80, v80
	v_exp_f32_e32 v81, v81
	v_exp_f32_e32 v82, v82
	v_exp_f32_e32 v83, v83
	v_add_f32_e32 v252, v104, v252
	v_add_f32_e32 v253, v105, v253
	v_cvt_pk_bf16_f32 v104, v104, v105
	v_add_f32_e32 v252, v106, v252
	v_add_f32_e32 v253, v107, v253
	v_cvt_pk_bf16_f32 v105, v106, v107
	v_mfma_f32_32x32x16_bf16 v[32:47], v[168:171], v[112:115], v[32:47]
	v_exp_f32_e32 v84, v84
	v_exp_f32_e32 v85, v85
	v_exp_f32_e32 v86, v86
	v_exp_f32_e32 v87, v87
	v_add_f32_e32 v252, v108, v252
	v_add_f32_e32 v253, v109, v253
	v_cvt_pk_bf16_f32 v106, v108, v109
	v_add_f32_e32 v252, v110, v252
	v_add_f32_e32 v253, v111, v253
	v_cvt_pk_bf16_f32 v107, v110, v111
	v_mfma_f32_32x32x16_bf16 v[48:63], v[164:167], v[120:123], v[48:63]
	v_exp_f32_e32 v88, v88
	v_exp_f32_e32 v89, v89
	v_exp_f32_e32 v90, v90
	v_exp_f32_e32 v91, v91
	v_mfma_f32_32x32x16_bf16 v[32:47], v[160:163], v[120:123], v[32:47]
	v_exp_f32_e32 v92, v92
	v_exp_f32_e32 v93, v93
	v_exp_f32_e32 v94, v94
	v_exp_f32_e32 v95, v95
	s_cmp_eq_u32 s52, s4
	s_cbranch_scc0 .LBB0_82
	v_add_f32_e32 v252, v80, v252
	v_add_f32_e32 v253, v81, v253
	v_cvt_pk_bf16_f32 v80, v80, v81
	v_add_f32_e32 v252, v82, v252
	v_add_f32_e32 v253, v83, v253
	v_cvt_pk_bf16_f32 v81, v82, v83
	v_add_f32_e32 v252, v84, v252
	v_add_f32_e32 v253, v85, v253
	v_cvt_pk_bf16_f32 v82, v84, v85
	v_add_f32_e32 v252, v86, v252
	v_add_f32_e32 v253, v87, v253
	v_cvt_pk_bf16_f32 v83, v86, v87
	v_add_f32_e32 v252, v88, v252
	v_add_f32_e32 v253, v89, v253
	v_cvt_pk_bf16_f32 v88, v88, v89
	v_add_f32_e32 v252, v90, v252
	v_add_f32_e32 v253, v91, v253
	v_cvt_pk_bf16_f32 v89, v90, v91
	v_add_f32_e32 v252, v92, v252
	v_add_f32_e32 v253, v93, v253
	v_cvt_pk_bf16_f32 v90, v92, v93
	v_add_f32_e32 v252, v94, v252
	v_add_f32_e32 v253, v95, v253
	v_cvt_pk_bf16_f32 v91, v94, v95
	v_add_f32_e32 v252, v252, v253
	v_add_f32_e32 v194, v194, v252
	v_mfma_f32_32x32x16_bf16 v[64:79], v[188:191], v[96:99], v[64:79]
	v_mfma_f32_32x32x16_bf16 v[16:31], v[184:187], v[96:99], v[16:31]
	v_mfma_f32_32x32x16_bf16 v[64:79], v[180:183], v[104:107], v[64:79]
	v_mfma_f32_32x32x16_bf16 v[16:31], v[176:179], v[104:107], v[16:31]
	v_mfma_f32_32x32x16_bf16 v[64:79], v[172:175], v[80:83], v[64:79]
	v_mfma_f32_32x32x16_bf16 v[16:31], v[168:171], v[80:83], v[16:31]
	v_mfma_f32_32x32x16_bf16 v[64:79], v[164:167], v[88:91], v[64:79]
	v_mfma_f32_32x32x16_bf16 v[16:31], v[160:163], v[88:91], v[16:31]
	s_lshl_b32 s4, s35, 14
	s_add_i32 s5, s4, 32
	v_add_u32_e32 v92, s5, v217
	v_add_u32_e32 v180, v92, v219
	v_add_u32_e32 v196, v92, v218
	v_add_u32_e32 v197, v92, v216
	v_add_u32_e32 v198, v92, v215
	s_waitcnt vmcnt(4)
	s_barrier
	ds_read_b128 v[80:83], v180
	ds_read_b128 v[84:87], v180 offset:4096
	ds_read_b128 v[160:163], v196
	ds_read_b128 v[164:167], v196 offset:4096
	ds_read_b128 v[88:91], v197
	ds_read_b128 v[168:171], v197 offset:4096
	ds_read_b128 v[172:175], v198
	ds_read_b128 v[176:179], v198 offset:4096
	s_waitcnt lgkmcnt(0)
	v_mfma_f32_32x32x16_bf16 v[128:143], v[80:83], v[152:155], v[0:15]
	v_mfma_f32_32x32x16_bf16 v[96:111], v[88:91], v[156:159], v[0:15]
	v_mfma_f32_32x32x16_bf16 v[112:127], v[84:87], v[152:155], v[0:15]
	v_mfma_f32_32x32x16_bf16 v[80:95], v[168:171], v[156:159], v[0:15]
	v_mfma_f32_32x32x16_bf16 v[128:143], v[160:163], v[144:147], v[128:143]
	v_mfma_f32_32x32x16_bf16 v[96:111], v[172:175], v[148:151], v[96:111]
	v_mfma_f32_32x32x16_bf16 v[112:127], v[164:167], v[144:147], v[112:127]
	v_mfma_f32_32x32x16_bf16 v[80:95], v[176:179], v[148:151], v[80:95]
	ds_read_b128 v[188:191], v180 offset:8192
	ds_read_b128 v[184:187], v180 offset:12288
	ds_read_b128 v[180:183], v196 offset:8192
	ds_read_b128 v[176:179], v196 offset:12288
	ds_read_b128 v[172:175], v197 offset:8192
	ds_read_b128 v[168:171], v197 offset:12288
	ds_read_b128 v[164:167], v198 offset:8192
	ds_read_b128 v[160:163], v198 offset:12288
	s_nop 0
	v_exp_f32_e32 v128, v128
	v_exp_f32_e32 v129, v129
	v_exp_f32_e32 v130, v130
	v_exp_f32_e32 v131, v131
	v_exp_f32_e32 v132, v132
	v_exp_f32_e32 v133, v133
	v_exp_f32_e32 v134, v134
	v_exp_f32_e32 v135, v135
	v_add_f32_e64 v196, v128, 0
	v_add_f32_e64 v197, v129, 0
	v_cvt_pk_bf16_f32 v128, v128, v129
	v_add_f32_e64 v196, v130, v196
	v_add_f32_e64 v197, v131, v197
	v_cvt_pk_bf16_f32 v129, v130, v131
	v_cvt_pk_bf16_f32 v130, v132, v133
	v_cvt_pk_bf16_f32 v131, v134, v135
	v_add_f32_e64 v196, v132, v196
	v_add_f32_e64 v197, v133, v197
	v_exp_f32_e32 v136, v136
	s_waitcnt lgkmcnt(0)
; #define MFMA(a, b, c) __builtin_amdgcn_mfma_f32_32x32x16_bf16((a), (b), (c), 0, 0, 0)
; #define LOAD_VF() do { \
;             __builtin_amdgcn_sched_barrier(0); \
;             _Pragma("unroll") for (int s = 0; s < 4; ++s) \
;                 _Pragma("unroll") for (int dt = 0; dt < 2; ++dt) vf[2 * s + dt] = ldv_frag(sv, 32 * dt + r, 2 * s + h, xr); \
;             __builtin_amdgcn_sched_barrier(0); } while (0)
; template <int KIND>
; DI void attn_unit(const Params& p, int l, int b, int head, int qt, int qcol, int kcol, int vfeat, int gcol, int mixcol,
;                   int t1, int n1, int t2, int n2, char* smem) {
;     ...
;             if (KIND == 0) {
;                 f32x16 S0[2], S1[2];
; #pragma unroll
;                 for (int t = 0; t < 2; ++t) { S0[t] = MFMA(kf[t], qf[0], cz); S1[t] = MFMA(kf[4 + t], qf[2], cz); }
; #pragma unroll
;                 for (int t = 0; t < 2; ++t) { S0[t] = MFMA(kf[2 + t], qf[1], S0[t]); S1[t] = MFMA(kf[6 + t], qf[3], S1[t]); }
;                 LOAD_VF();
;                 softmax_tile(S0, l0);
;                 pv_tile(S0, O0, vf);
;                 softmax_tile(S1, l1);
;                 pv_tile(S1, O1, vf);
	v_mfma_f32_32x32x16_bf16 v[48:63], v[188:191], v[128:131], v[48:63]
	v_exp_f32_e32 v137, v137
	v_exp_f32_e32 v138, v138
	v_exp_f32_e32 v139, v139
	v_exp_f32_e32 v132, v140
	v_exp_f32_e32 v133, v141
	v_exp_f32_e32 v140, v142
	v_exp_f32_e32 v141, v143
	v_mfma_f32_32x32x16_bf16 v[32:47], v[184:187], v[128:131], v[32:47]
	v_add_f32_e64 v134, v134, v196
	v_add_f32_e64 v135, v135, v197
	v_cvt_pk_bf16_f32 v128, v136, v137
	v_cvt_pk_bf16_f32 v129, v138, v139
	v_cvt_pk_bf16_f32 v130, v132, v133
	v_cvt_pk_bf16_f32 v131, v140, v141
	v_add_f32_e64 v134, v136, v134
	v_add_f32_e64 v135, v137, v135
	v_exp_f32_e32 v112, v112
	v_mfma_f32_32x32x16_bf16 v[48:63], v[180:183], v[128:131], v[48:63]
	v_add_f32_e64 v134, v138, v134
	v_add_f32_e64 v135, v139, v135
	v_exp_f32_e32 v113, v113
	v_add_f32_e64 v134, v132, v134
	v_add_f32_e64 v135, v133, v135
	v_exp_f32_e32 v116, v116
	v_add_f32_e64 v132, v140, v134
	v_add_f32_e64 v133, v141, v135
	v_exp_f32_e32 v134, v114
	v_exp_f32_e32 v135, v115
	v_mfma_f32_32x32x16_bf16 v[32:47], v[176:179], v[128:131], v[32:47]
	v_exp_f32_e32 v117, v117
	v_exp_f32_e32 v118, v118
	v_exp_f32_e32 v119, v119
	v_add_f32_e64 v132, v112, v132
	v_add_f32_e64 v133, v113, v133
	v_cvt_pk_bf16_f32 v112, v112, v113
	v_cvt_pk_bf16_f32 v113, v134, v135
	v_cvt_pk_bf16_f32 v114, v116, v117
	v_cvt_pk_bf16_f32 v115, v118, v119
	v_add_f32_e64 v128, v134, v132
	v_add_f32_e64 v129, v135, v133
	v_exp_f32_e32 v120, v120
	v_mfma_f32_32x32x16_bf16 v[48:63], v[172:175], v[112:115], v[48:63]
	v_add_f32_e64 v116, v116, v128
	v_add_f32_e64 v117, v117, v129
	v_exp_f32_e32 v121, v121
	v_add_f32_e64 v116, v118, v116
	v_add_f32_e64 v117, v119, v117
	v_exp_f32_e32 v118, v122
	v_exp_f32_e32 v119, v123
	v_exp_f32_e32 v122, v124
	v_exp_f32_e32 v123, v125
	v_mfma_f32_32x32x16_bf16 v[32:47], v[168:171], v[112:115], v[32:47]
	v_exp_f32_e32 v124, v126
	v_exp_f32_e32 v125, v127
	v_exp_f32_e32 v96, v96
	v_exp_f32_e32 v97, v97
	v_exp_f32_e32 v98, v98
	v_exp_f32_e32 v99, v99
	v_exp_f32_e32 v100, v100
	v_exp_f32_e32 v101, v101
	v_exp_f32_e32 v102, v102
	v_exp_f32_e32 v103, v103
	v_cvt_pk_bf16_f32 v112, v120, v121
	v_cvt_pk_bf16_f32 v113, v118, v119
	v_cvt_pk_bf16_f32 v114, v122, v123
	v_cvt_pk_bf16_f32 v115, v124, v125
	v_exp_f32_e32 v104, v104
	v_exp_f32_e32 v105, v105
	v_mfma_f32_32x32x16_bf16 v[48:63], v[164:167], v[112:115], v[48:63]
	v_exp_f32_e32 v106, v106
	v_exp_f32_e32 v107, v107
	v_exp_f32_e32 v80, v80
	v_exp_f32_e32 v81, v81
	v_exp_f32_e32 v82, v82
	v_exp_f32_e32 v83, v83
	v_exp_f32_e32 v84, v84
	v_mfma_f32_32x32x16_bf16 v[32:47], v[160:163], v[112:115], v[32:47]
	v_add_f32_e64 v112, v96, 0
	v_add_f32_e64 v113, v97, 0
	v_cvt_pk_bf16_f32 v96, v96, v97
	v_add_f32_e64 v112, v98, v112
	v_add_f32_e64 v113, v99, v113
	v_cvt_pk_bf16_f32 v97, v98, v99
	v_cvt_pk_bf16_f32 v98, v100, v101
	v_cvt_pk_bf16_f32 v99, v102, v103
	v_add_f32_e64 v112, v100, v112
	v_add_f32_e64 v113, v101, v113
	v_exp_f32_e32 v100, v108
	v_mfma_f32_32x32x16_bf16 v[64:79], v[188:191], v[96:99], v[64:79]
	v_exp_f32_e32 v101, v109
	v_add_f32_e64 v112, v102, v112
	v_add_f32_e64 v113, v103, v113
	v_exp_f32_e32 v102, v110
	v_exp_f32_e32 v103, v111
	v_add_f32_e64 v112, v104, v112
	v_add_f32_e64 v113, v105, v113
	v_exp_f32_e32 v85, v85
	v_add_f32_e64 v112, v106, v112
	v_add_f32_e64 v113, v107, v113
	v_mfma_f32_32x32x16_bf16 v[16:31], v[184:187], v[96:99], v[16:31]
	v_add_f32_e64 v108, v100, v112
	v_add_f32_e64 v109, v101, v113
	v_cvt_pk_bf16_f32 v98, v100, v101
	v_add_f32_e64 v96, v102, v108
	v_add_f32_e64 v97, v103, v109
	v_cvt_pk_bf16_f32 v99, v102, v103
	v_add_f32_e64 v108, v80, v96
	v_add_f32_e64 v109, v81, v97
	v_cvt_pk_bf16_f32 v96, v104, v105
	v_cvt_pk_bf16_f32 v97, v106, v107
	v_exp_f32_e32 v86, v86
	v_exp_f32_e32 v87, v87
	v_mfma_f32_32x32x16_bf16 v[64:79], v[180:183], v[96:99], v[64:79]
	v_add_f32_e64 v100, v82, v108
	v_add_f32_e64 v101, v83, v109
	v_exp_f32_e32 v88, v88
	v_add_f32_e64 v100, v84, v100
	v_add_f32_e64 v101, v85, v101
	v_exp_f32_e32 v89, v89
	v_cvt_pk_bf16_f32 v80, v80, v81
	v_cvt_pk_bf16_f32 v81, v82, v83
	v_cvt_pk_bf16_f32 v82, v84, v85
	v_mfma_f32_32x32x16_bf16 v[16:31], v[176:179], v[96:99], v[16:31]
	v_cvt_pk_bf16_f32 v83, v86, v87
	v_add_f32_e64 v96, v86, v100
	v_add_f32_e64 v97, v87, v101
	v_exp_f32_e32 v86, v90
	v_exp_f32_e32 v87, v91
	v_exp_f32_e32 v90, v92
	v_exp_f32_e32 v91, v93
	v_exp_f32_e32 v92, v94
	v_mfma_f32_32x32x16_bf16 v[64:79], v[172:175], v[80:83], v[64:79]
	v_exp_f32_e32 v93, v95
	s_addk_i32 s4, 0x4000
	v_add_f32_e64 v84, v88, v96
	v_add_f32_e64 v85, v89, v97
	s_cmp_lg_u32 s35, 2
	s_cselect_b32 s4, s4, 0
	s_add_i32 s4, s4, 32
	s_waitcnt vmcnt(0)
	v_mfma_f32_32x32x16_bf16 v[16:31], v[168:171], v[80:83], v[16:31]
	v_add_f32_e64 v80, v86, v84
	v_add_f32_e64 v81, v87, v85
	v_cvt_pk_bf16_f32 v82, v90, v91
	v_add_f32_e64 v80, v90, v80
	v_add_f32_e64 v81, v91, v81
	v_cvt_pk_bf16_f32 v83, v92, v93
	v_add_f32_e64 v168, v92, v80
	v_add_f32_e64 v169, v93, v81
	v_cvt_pk_bf16_f32 v80, v88, v89
	v_add_u32_e32 v88, s4, v217
	v_cvt_pk_bf16_f32 v81, v86, v87
	v_add_u32_e32 v174, v88, v219
	v_add_u32_e32 v175, v88, v218
	v_add_u32_e32 v176, v88, v216
	v_add_u32_e32 v177, v88, v215
	v_mfma_f32_32x32x16_bf16 v[64:79], v[164:167], v[80:83], v[64:79]
	s_barrier
; #define MFMA(a, b, c) __builtin_amdgcn_mfma_f32_32x32x16_bf16((a), (b), (c), 0, 0, 0)
; #define LOAD_VF() do { \
;             __builtin_amdgcn_sched_barrier(0); \
;             _Pragma("unroll") for (int s = 0; s < 4; ++s) \
;                 _Pragma("unroll") for (int dt = 0; dt < 2; ++dt) vf[2 * s + dt] = ldv_frag(sv, 32 * dt + r, 2 * s + h, xr); \
;             __builtin_amdgcn_sched_barrier(0); } while (0)
; template <int KIND>
; DI void attn_unit(const Params& p, int l, int b, int head, int qt, int qcol, int kcol, int vfeat, int gcol, int mixcol,
;                   int t1, int n1, int t2, int n2, char* smem) {
;     ...
;             if (KIND == 0) {
;                 f32x16 S0[2], S1[2];
; #pragma unroll
;                 for (int t = 0; t < 2; ++t) { S0[t] = MFMA(kf[t], qf[0], cz); S1[t] = MFMA(kf[4 + t], qf[2], cz); }
; #pragma unroll
;                 for (int t = 0; t < 2; ++t) { S0[t] = MFMA(kf[2 + t], qf[1], S0[t]); S1[t] = MFMA(kf[6 + t], qf[3], S1[t]); }
;                 LOAD_VF();
;                 softmax_tile(S0, l0);
;                 pv_tile(S0, O0, vf);
;                 softmax_tile(S1, l1);
;                 pv_tile(S1, O1, vf);
; template <int Q>
; DI void attn_queue(const Params& p, int l, char* smem, int* s_unit, int cb) {
;     ...
;     for (;;) {
;         if (threadIdx.x == 0) *s_unit = (int)atomicAdd(p.ctr + cb + l * 4 + Q, 1u);
;         __syncthreads();
	s_mov_b64 exec, s[54:55]
	s_load_dwordx2 s[100:101], s[0:1], 0x100
	s_lshl_b32 m0, s48, 2
	v_mov_b32_e32 v253, 1
	s_waitcnt lgkmcnt(0)
	s_add_u32 s100, s100, m0
	s_addc_u32 s101, s101, 0
	global_atomic_add v253, v193, v253, s[100:101] sc0
	s_mov_b64 exec, -1
	ds_read_b128 v[84:87], v174
	ds_read_b128 v[128:131], v174 offset:4096
	ds_read_b128 v[132:135], v175
	ds_read_b128 v[136:139], v175 offset:4096
	ds_read_b128 v[96:99], v176
	ds_read_b128 v[140:143], v176 offset:4096
	ds_read_b128 v[164:167], v177
	ds_read_b128 v[170:173], v177 offset:4096
	v_add_f32_e64 v116, v120, v116
	v_add_f32_e64 v117, v121, v117
	s_nop 0
	v_add_f32_e64 v116, v118, v116
	v_add_f32_e64 v117, v119, v117
	v_mfma_f32_32x32x16_bf16 v[16:31], v[160:163], v[80:83], v[16:31]
	v_add_f32_e64 v116, v122, v116
	v_add_f32_e64 v117, v123, v117
	v_add_f32_e64 v196, v124, v116
	v_add_f32_e64 v197, v125, v117
	s_waitcnt lgkmcnt(0)
	v_mfma_f32_32x32x16_bf16 v[112:127], v[84:87], v[152:155], v[0:15]
	v_mfma_f32_32x32x16_bf16 v[80:95], v[96:99], v[156:159], v[0:15]
	v_mfma_f32_32x32x16_bf16 v[96:111], v[128:131], v[152:155], v[0:15]
	v_mfma_f32_32x32x16_bf16 v[0:15], v[140:143], v[156:159], v[0:15]
	v_mfma_f32_32x32x16_bf16 v[112:127], v[132:135], v[144:147], v[112:127]
	v_mfma_f32_32x32x16_bf16 v[80:95], v[164:167], v[148:151], v[80:95]
	v_mfma_f32_32x32x16_bf16 v[96:111], v[136:139], v[144:147], v[96:111]
	v_mfma_f32_32x32x16_bf16 v[0:15], v[170:173], v[148:151], v[0:15]
	ds_read_b128 v[156:159], v174 offset:8192
	ds_read_b128 v[152:155], v174 offset:12288
	ds_read_b128 v[148:151], v175 offset:8192
	ds_read_b128 v[144:147], v175 offset:12288
	ds_read_b128 v[140:143], v176 offset:8192
	ds_read_b128 v[136:139], v176 offset:12288
	ds_read_b128 v[132:135], v177 offset:8192
	ds_read_b128 v[128:131], v177 offset:12288
	s_nop 0
	v_exp_f32_e32 v112, v112
	v_exp_f32_e32 v113, v113
	v_exp_f32_e32 v114, v114
	v_exp_f32_e32 v115, v115
	v_exp_f32_e32 v116, v116
	v_exp_f32_e32 v117, v117
	v_exp_f32_e32 v118, v118
	v_exp_f32_e32 v119, v119
	v_add_f32_e64 v160, v112, 0
	v_add_f32_e64 v161, v113, 0
	v_cvt_pk_bf16_f32 v112, v112, v113
	v_add_f32_e64 v160, v114, v160
	v_add_f32_e64 v161, v115, v161
	v_cvt_pk_bf16_f32 v113, v114, v115
	v_cvt_pk_bf16_f32 v114, v116, v117
	v_cvt_pk_bf16_f32 v115, v118, v119
	v_exp_f32_e32 v120, v120
	v_exp_f32_e32 v121, v121
	s_waitcnt lgkmcnt(0)
	v_mfma_f32_32x32x16_bf16 v[48:63], v[156:159], v[112:115], v[48:63]
	v_exp_f32_e32 v122, v122
	v_exp_f32_e32 v123, v123
	v_exp_f32_e32 v124, v124
	v_exp_f32_e32 v125, v125
	v_exp_f32_e32 v126, v126
	v_exp_f32_e32 v127, v127
	v_add_f32_e64 v160, v116, v160
	v_add_f32_e64 v161, v117, v161
	v_mfma_f32_32x32x16_bf16 v[32:47], v[152:155], v[112:115], v[32:47]
	v_add_f32_e64 v160, v118, v160
	v_add_f32_e64 v161, v119, v161
	v_exp_f32_e32 v118, v96
	v_add_f32_e64 v160, v120, v160
	v_add_f32_e64 v161, v121, v161
	v_exp_f32_e32 v119, v97
	v_add_f32_e64 v116, v122, v160
	v_add_f32_e64 v117, v123, v161
	v_exp_f32_e32 v160, v98
	v_exp_f32_e32 v161, v99
	v_cvt_pk_bf16_f32 v96, v120, v121
	v_cvt_pk_bf16_f32 v97, v122, v123
	v_cvt_pk_bf16_f32 v98, v124, v125
	v_cvt_pk_bf16_f32 v99, v126, v127
	v_add_f32_e64 v116, v124, v116
	v_add_f32_e64 v117, v125, v117
	v_exp_f32_e32 v100, v100
	v_mfma_f32_32x32x16_bf16 v[48:63], v[148:151], v[96:99], v[48:63]
	v_exp_f32_e32 v101, v101
	v_add_f32_e64 v116, v126, v116
	v_add_f32_e64 v117, v127, v117
	v_exp_f32_e32 v102, v102
	v_exp_f32_e32 v103, v103
	v_add_f32_e64 v112, v118, v116
	v_add_f32_e64 v113, v119, v117
	v_exp_f32_e32 v104, v104
	v_exp_f32_e32 v105, v105
	v_mfma_f32_32x32x16_bf16 v[32:47], v[144:147], v[96:99], v[32:47]
	v_add_f32_e64 v112, v160, v112
	v_add_f32_e64 v113, v161, v113
	v_exp_f32_e32 v106, v106
	v_exp_f32_e32 v107, v107
	v_add_f32_e64 v112, v100, v112
	v_add_f32_e64 v113, v101, v113
	v_exp_f32_e32 v108, v108
	v_add_f32_e64 v112, v102, v112
	v_add_f32_e64 v113, v103, v113
	v_cvt_pk_bf16_f32 v96, v118, v119
	v_cvt_pk_bf16_f32 v97, v160, v161
	v_cvt_pk_bf16_f32 v98, v100, v101
	v_cvt_pk_bf16_f32 v99, v102, v103
	v_exp_f32_e32 v109, v109
	v_exp_f32_e32 v100, v110
	v_mfma_f32_32x32x16_bf16 v[48:63], v[140:143], v[96:99], v[48:63]
	v_exp_f32_e32 v101, v111
	v_add_f32_e64 v102, v104, v112
	v_add_f32_e64 v103, v105, v113
	v_exp_f32_e32 v84, v84
	v_add_f32_e64 v102, v106, v102
	v_add_f32_e64 v103, v107, v103
	v_exp_f32_e32 v85, v85
	v_add_f32_e64 v102, v108, v102
	v_add_f32_e64 v103, v109, v103
	v_exp_f32_e32 v86, v86
	v_mfma_f32_32x32x16_bf16 v[32:47], v[136:139], v[96:99], v[32:47]
	v_cvt_pk_bf16_f32 v96, v104, v105
	v_exp_f32_e32 v104, v80
	v_exp_f32_e32 v105, v81
	v_cvt_pk_bf16_f32 v97, v106, v107
	v_exp_f32_e32 v106, v82
	v_exp_f32_e32 v107, v83
	v_exp_f32_e32 v87, v87
	v_add_f32_e64 v102, v100, v102
	v_add_f32_e64 v103, v101, v103
	v_add_f32_e64 v82, v104, 0
	v_add_f32_e64 v83, v105, 0
	v_exp_f32_e32 v88, v88
	v_exp_f32_e32 v89, v89
	v_mov_b32_e32 v110, v196
	v_mov_b32_e32 v111, v102
	v_mov_b32_e32 v102, v197
	v_add_f32_e64 v82, v106, v82
	v_add_f32_e64 v83, v107, v83
	v_exp_f32_e32 v90, v90
	v_exp_f32_e32 v91, v91
	v_cvt_pk_bf16_f32 v99, v100, v101
	v_add_f32_e64 v100, v110, v102
	v_add_f32_e64 v101, v111, v103
	v_add_f32_e64 v82, v84, v82
	v_add_f32_e64 v83, v85, v83
	v_exp_f32_e32 v92, v92
	v_exp_f32_e32 v93, v93
	s_add_u32 s7, s29, s7
	v_pk_add_f32 v[102:103], v[194:195], v[100:101] op_sel:[1,0] op_sel_hi:[0,1]
	v_add_f32_e64 v82, v86, v82
	v_add_f32_e64 v83, v87, v83
	s_addc_u32 s9, s9, 0
	s_add_i32 s8, s8, 0x36000
	s_lshl_b64 s[4:5], s[60:61], 2
	v_cvt_pk_bf16_f32 v98, v108, v109
	v_pk_add_f32 v[80:81], v[102:103], v[100:101] op_sel:[0,1] op_sel_hi:[1,0]
	v_add_f32_e64 v82, v88, v82
; #define MFMA(a, b, c) __builtin_amdgcn_mfma_f32_32x32x16_bf16((a), (b), (c), 0, 0, 0)
; DI int otid() { int t = threadIdx.x; asm volatile("" : "+v"(t)); return t; }
; DI float xsum32(float x) { const unsigned u = __float_as_uint(x); const auto r2 = __builtin_amdgcn_permlane32_swap(u, u, false, false); return __uint_as_float(r2[0]) + __uint_as_float(r2[1]); }
; DI void pv_tile(const f32x16 (&S)[2], f32x16 (&O)[2], const bf16x8 (&vf)[8]) {
; #pragma unroll
;     for (int s = 0; s < 4; ++s) {
;         const bf16x8 pf = pack8(S[s >> 1], s & 1);
; #pragma unroll
;         for (int dt = 0; dt < 2; ++dt) O[dt] = MFMA(vf[2 * s + dt], pf, O[dt]);
;     }
; template <int KIND>
; DI void attn_unit(const Params& p, int l, int b, int head, int qt, int qcol, int kcol, int vfeat, int gcol, int mixcol,
;                   int t1, int n1, int t2, int n2, char* smem) {
;     ...
;     l0 = xsum32(l0);
;     const float inv0 = 1.f / l0;
;     const int tid_e = otid();
;     const size_t qrow_e = (size_t)b * TPB + qt * 128 + 32 * (tid_e >> 6) + (tid_e & 31);
;     bf16_t* orow = p.hmix + ((size_t)(mixcol >> 5) * NTOK + qrow_e) * 32;
;     const bf16_t* grow = p.qkv + ((size_t)(gcol >> 6) * NTOK + qrow_e) * 64;
;     if (KIND == 0) {
;         l1 = xsum32(l1);
;         const float lam = p.lam[l];
;         const float inv1 = lam / l1;
;         float ss = 0.f;
; #pragma unroll
;         for (int t = 0; t < 2; ++t)
; #pragma unroll
;             for (int e = 0; e < 16; ++e) { const float o = O0[t][e] * inv0 - O1[t][e] * inv1; O0[t][e] = o; ss += o * o; }
;         ss = xsum32(ss);
;         const float rstd = rsqrtf(ss * (1.f / 64.f) + EPS) * p.lam[4 + l];
	v_add_f32_e64 v83, v89, v83
	s_add_u32 s4, s50, s4
	v_mfma_f32_32x32x16_bf16 v[48:63], v[132:135], v[96:99], v[48:63]
	v_mov_b32_e32 v81, v200
	s_addc_u32 s5, s51, s5
	v_cvt_pk_bf16_f32 v84, v84, v85
	v_cvt_pk_bf16_f32 v85, v86, v87
	v_exp_f32_e32 v94, v94
	v_exp_f32_e32 v95, v95
	v_mfma_f32_32x32x16_bf16 v[32:47], v[128:131], v[96:99], v[32:47]
	v_add_f32_e64 v96, v90, v82
	v_add_f32_e64 v97, v91, v83
	v_exp_f32_e32 v98, v0
	v_exp_f32_e32 v99, v1
	v_add_f32_e64 v0, v92, v96
	v_add_f32_e64 v1, v93, v97
	global_load_dword v96, v193, s[4:5]
	v_cvt_pk_bf16_f32 v82, v104, v105
	v_cvt_pk_bf16_f32 v83, v106, v107
	v_exp_f32_e32 v100, v2
	v_exp_f32_e32 v101, v3
	v_mfma_f32_32x32x16_bf16 v[64:79], v[156:159], v[82:85], v[64:79]
	v_exp_f32_e32 v86, v4
	v_exp_f32_e32 v87, v5
	v_cvt_pk_bf16_f32 v2, v88, v89
	v_cvt_pk_bf16_f32 v3, v90, v91
	v_cvt_pk_bf16_f32 v4, v92, v93
	v_cvt_pk_bf16_f32 v5, v94, v95
	v_add_f32_e64 v0, v94, v0
	v_add_f32_e64 v1, v95, v1
	v_mfma_f32_32x32x16_bf16 v[16:31], v[152:155], v[82:85], v[16:31]
	v_exp_f32_e32 v6, v6
	v_exp_f32_e32 v7, v7
	v_add_f32_e64 v0, v98, v0
	v_add_f32_e64 v1, v99, v1
	v_exp_f32_e32 v8, v8
	v_exp_f32_e32 v9, v9
	v_add_f32_e64 v0, v100, v0
	v_add_f32_e64 v1, v101, v1
	v_exp_f32_e32 v10, v10
	v_mfma_f32_32x32x16_bf16 v[64:79], v[148:151], v[2:5], v[64:79]
	v_exp_f32_e32 v11, v11
	v_add_f32_e64 v82, v86, v0
	v_add_f32_e64 v83, v87, v1
	v_exp_f32_e32 v12, v12
	v_exp_f32_e32 v13, v13
	v_add_f32_e64 v82, v6, v82
	v_add_f32_e64 v83, v7, v83
	v_ashrrev_i32_e32 v0, 1, v81
	v_and_b32_e32 v0, 0xffffffe0, v0
	v_mfma_f32_32x32x16_bf16 v[16:31], v[144:147], v[2:5], v[16:31]
	v_cvt_pk_bf16_f32 v5, v6, v7
	v_exp_f32_e32 v6, v14
	v_exp_f32_e32 v7, v15
	v_add_f32_e64 v14, v8, v82
	v_add_f32_e64 v15, v9, v83
	v_cvt_pk_bf16_f32 v2, v98, v99
	v_add_f32_e64 v14, v10, v14
	v_add_f32_e64 v15, v11, v15
	v_cvt_pk_bf16_f32 v3, v100, v101
	v_cvt_pk_bf16_f32 v4, v86, v87
	v_add_f32_e64 v14, v12, v14
	v_add_f32_e64 v15, v13, v15
	v_ashrrev_i32_e32 v1, 31, v0
	v_mfma_f32_32x32x16_bf16 v[64:79], v[140:143], v[2:5], v[64:79]
	v_add_f32_e64 v14, v6, v14
	v_add_f32_e64 v15, v7, v15
	v_and_or_b32 v84, v81, 31, s7
	v_mov_b32_e32 v85, s9
	v_lshl_add_u64 v[84:85], v[84:85], 0, v[0:1]
	s_mov_b32 s9, s75
	v_lshl_add_u64 v[0:1], v[84:85], 0, s[8:9]
	v_mov_b32_e32 v82, v168
	v_mfma_f32_32x32x16_bf16 v[16:31], v[136:139], v[2:5], v[16:31]
	v_cvt_pk_bf16_f32 v5, v6, v7
	v_mov_b32_e32 v6, v80
	s_nop 1
	v_permlane32_swap_b32_e32 v80, v6
	v_cvt_pk_bf16_f32 v2, v8, v9
	v_add_f32_e32 v8, v80, v6
	v_div_scale_f32 v9, s[8:9], v8, v8, 1.0
	v_cvt_pk_bf16_f32 v3, v10, v11
	v_rcp_f32_e32 v10, v9
	v_cvt_pk_bf16_f32 v4, v12, v13
	v_mov_b32_e32 v83, v14
	v_mov_b32_e32 v14, v169
	v_mfma_f32_32x32x16_bf16 v[64:79], v[132:135], v[2:5], v[64:79]
	v_add_f32_e64 v14, v82, v14
	v_add_f32_e64 v15, v83, v15
	global_load_dword v80, v193, s[4:5] offset:16
	v_add_f32_e64 v6, v194, v14
	v_add_f32_e64 v7, v195, v15
	v_lshlrev_b64 v[0:1], 7, v[0:1]
	v_pk_add_f32 v[6:7], v[6:7], v[14:15] op_sel:[0,1] op_sel_hi:[1,0]
	v_lshl_add_u64 v[0:1], s[40:41], 0, v[0:1]
	v_lshlrev_b32_e32 v88, 3, v214
	v_mfma_f32_32x32x16_bf16 v[16:31], v[128:131], v[2:5], v[16:31]
	v_fma_f32 v2, -v9, v10, 1.0
	v_fmac_f32_e32 v10, v2, v10
	v_div_scale_f32 v2, vcc, 1.0, v8, 1.0
	v_mul_f32_e32 v3, v2, v10
	v_fma_f32 v4, -v9, v3, v2
	v_fmac_f32_e32 v3, v4, v10
	v_fma_f32 v2, -v9, v3, v2
	v_div_fmas_f32 v2, v2, v10, v3
	v_div_fixup_f32 v8, v2, v8, 1.0
	v_mov_b32_e32 v2, v6
	s_nop 1
	v_permlane32_swap_b32_e32 v6, v2
	v_add_f32_e32 v4, v6, v2
	s_waitcnt vmcnt(0)
	v_div_scale_f32 v5, s[4:5], v4, v4, v96
	v_rcp_f32_e32 v6, v5
	v_mov_b32_e32 v89, v193
	v_lshl_add_u64 v[0:1], v[0:1], 0, v[88:89]
	s_mul_i32 s6, s6, 0x9000
	v_fma_f32 v7, -v5, v6, 1.0
	s_mov_b32 s7, s75
	v_fmac_f32_e32 v6, v7, v6
	v_div_scale_f32 v7, vcc, v96, v4, v96
	global_load_dwordx2 v[90:91], v[0:1], off
	v_lshl_add_u64 v[2:3], v[84:85], 0, s[6:7]
	v_mul_f32_e32 v9, v7, v6
	s_load_dwordx2 s[4:5], s[0:1], 0xb8
	s_load_dwordx2 s[6:7], s[0:1], 0x78
	v_fma_f32 v10, -v5, v9, v7
	v_fmac_f32_e32 v9, v10, v6
	v_fma_f32 v5, -v5, v9, v7
	v_lshlrev_b64 v[2:3], 6, v[2:3]
	v_div_fmas_f32 v5, v5, v6, v9
	v_div_fixup_f32 v10, v5, v4, v96
	s_waitcnt lgkmcnt(0)
	v_lshl_add_u64 v[2:3], s[4:5], 0, v[2:3]
	s_add_u32 s4, s6, s46
	s_addc_u32 s5, s7, s47
	v_pk_mul_f32 v[4:5], v[66:67], v[10:11] op_sel_hi:[1,0]
	v_pk_mul_f32 v[16:17], v[16:17], v[10:11] op_sel_hi:[1,0]
	v_pk_fma_f32 v[14:15], v[50:51], v[8:9], v[4:5] op_sel_hi:[1,0,1] neg_lo:[0,0,1] neg_hi:[0,0,1]
	global_load_dwordx4 v[4:7], v192, s[4:5]
	v_pk_mul_f32 v[50:51], v[64:65], v[10:11] op_sel_hi:[1,0]
	v_mul_f32_e32 v64, v15, v15
	v_pk_fma_f32 v[48:49], v[48:49], v[8:9], v[50:51] op_sel_hi:[1,0,1] neg_lo:[0,0,1] neg_hi:[0,0,1]
	v_pk_mul_f32 v[18:19], v[18:19], v[10:11] op_sel_hi:[1,0]
	v_mul_f32_e32 v50, v49, v49
	v_pk_fma_f32 v[50:51], v[48:49], v[48:49], v[50:51] op_sel_hi:[1,1,0]
	v_pk_fma_f32 v[16:17], v[32:33], v[8:9], v[16:17] op_sel_hi:[1,0,1] neg_lo:[0,0,1] neg_hi:[0,0,1]
	v_pk_fma_f32 v[50:51], v[14:15], v[14:15], v[50:51]
	v_pk_fma_f32 v[18:19], v[34:35], v[8:9], v[18:19] op_sel_hi:[1,0,1] neg_lo:[0,0,1] neg_hi:[0,0,1]
	v_pk_add_f32 v[50:51], v[64:65], v[50:51] op_sel_hi:[0,1]
	v_pk_mul_f32 v[64:65], v[70:71], v[10:11] op_sel_hi:[1,0]
	v_mul_f32_e32 v34, v17, v17
	v_pk_fma_f32 v[54:55], v[54:55], v[8:9], v[64:65] op_sel_hi:[1,0,1] neg_lo:[0,0,1] neg_hi:[0,0,1]
	v_pk_mul_f32 v[64:65], v[68:69], v[10:11] op_sel_hi:[1,0]
	v_pk_mul_f32 v[20:21], v[20:21], v[10:11] op_sel_hi:[1,0]
	v_pk_fma_f32 v[52:53], v[52:53], v[8:9], v[64:65] op_sel_hi:[1,0,1] neg_lo:[0,0,1] neg_hi:[0,0,1]
; DI unsigned pk2(float a, float b) { f2_t v = {a, b}; bf2_t r = __builtin_convertvector(v, bf2_t); return __builtin_bit_cast(unsigned, r); }
; DI float bf2f(bf16_t v) { return __uint_as_float(((unsigned)v) << 16); }
; DI float xsum32(float x) { const unsigned u = __float_as_uint(x); const auto r2 = __builtin_amdgcn_permlane32_swap(u, u, false, false); return __uint_as_float(r2[0]) + __uint_as_float(r2[1]); }
; template <int KIND>
; DI void attn_unit(const Params& p, int l, int b, int head, int qt, int qcol, int kcol, int vfeat, int gcol, int mixcol,
;                   int t1, int n1, int t2, int n2, char* smem) {
;     ...
;         float ss = 0.f;
; #pragma unroll
;         for (int t = 0; t < 2; ++t)
; #pragma unroll
;             for (int e = 0; e < 16; ++e) { const float o = O0[t][e] * inv0 - O1[t][e] * inv1; O0[t][e] = o; ss += o * o; }
;         ss = xsum32(ss);
;         const float rstd = rsqrtf(ss * (1.f / 64.f) + EPS) * p.lam[4 + l];
;         const float* sw = p.subln + l * 64;
; #pragma unroll
;         for (int t = 0; t < 2; ++t)
; #pragma unroll
;             for (int q = 0; q < 4; ++q) {
;                 const int f = 32 * t + 8 * q + 4 * h;
;                 const float4 w4 = *(const float4*)(sw + f);
;                 const uint2 gg = *(const uint2*)(grow + f);
;                 const float g0 = bf2f((bf16_t)(gg.x & 0xffff)), g1 = bf2f((bf16_t)(gg.x >> 16)), g2 = bf2f((bf16_t)(gg.y & 0xffff)), g3 = bf2f((bf16_t)(gg.y >> 16));
;                 uint2 o;
;                 o.x = pk2(O0[t][4 * q + 0] * rstd * w4.x * g0, O0[t][4 * q + 1] * rstd * w4.y * g1);
;                 o.y = pk2(O0[t][4 * q + 2] * rstd * w4.z * g2, O0[t][4 * q + 3] * rstd * w4.w * g3);
;                 *(uint2*)(orow + (size_t)t * NTOK * 32 + 8 * q + 4 * h) = o;
;             }
	v_pk_fma_f32 v[20:21], v[36:37], v[8:9], v[20:21] op_sel_hi:[1,0,1] neg_lo:[0,0,1] neg_hi:[0,0,1]
	v_pk_fma_f32 v[50:51], v[52:53], v[52:53], v[50:51]
	v_mul_f32_e32 v64, v53, v53
	v_pk_add_f32 v[50:51], v[64:65], v[50:51] op_sel_hi:[0,1]
	v_pk_fma_f32 v[50:51], v[54:55], v[54:55], v[50:51]
	v_mul_f32_e32 v64, v55, v55
	v_pk_add_f32 v[50:51], v[64:65], v[50:51] op_sel_hi:[0,1]
	v_pk_mul_f32 v[64:65], v[74:75], v[10:11] op_sel_hi:[1,0]
	v_pk_mul_f32 v[22:23], v[22:23], v[10:11] op_sel_hi:[1,0]
	v_pk_fma_f32 v[58:59], v[58:59], v[8:9], v[64:65] op_sel_hi:[1,0,1] neg_lo:[0,0,1] neg_hi:[0,0,1]
	v_pk_mul_f32 v[64:65], v[72:73], v[10:11] op_sel_hi:[1,0]
	v_pk_fma_f32 v[22:23], v[38:39], v[8:9], v[22:23] op_sel_hi:[1,0,1] neg_lo:[0,0,1] neg_hi:[0,0,1]
	v_pk_fma_f32 v[56:57], v[56:57], v[8:9], v[64:65] op_sel_hi:[1,0,1] neg_lo:[0,0,1] neg_hi:[0,0,1]
	v_pk_mul_f32 v[24:25], v[24:25], v[10:11] op_sel_hi:[1,0]
	v_pk_fma_f32 v[50:51], v[56:57], v[56:57], v[50:51]
	v_mul_f32_e32 v64, v57, v57
	v_pk_add_f32 v[50:51], v[64:65], v[50:51] op_sel_hi:[0,1]
	v_pk_fma_f32 v[50:51], v[58:59], v[58:59], v[50:51]
	v_mul_f32_e32 v64, v59, v59
	v_pk_add_f32 v[50:51], v[64:65], v[50:51] op_sel_hi:[0,1]
	v_pk_mul_f32 v[64:65], v[78:79], v[10:11] op_sel_hi:[1,0]
	v_pk_fma_f32 v[24:25], v[40:41], v[8:9], v[24:25] op_sel_hi:[1,0,1] neg_lo:[0,0,1] neg_hi:[0,0,1]
	v_pk_fma_f32 v[62:63], v[62:63], v[8:9], v[64:65] op_sel_hi:[1,0,1] neg_lo:[0,0,1] neg_hi:[0,0,1]
	v_pk_mul_f32 v[64:65], v[76:77], v[10:11] op_sel_hi:[1,0]
	v_pk_mul_f32 v[26:27], v[26:27], v[10:11] op_sel_hi:[1,0]
	v_pk_fma_f32 v[60:61], v[60:61], v[8:9], v[64:65] op_sel_hi:[1,0,1] neg_lo:[0,0,1] neg_hi:[0,0,1]
	v_pk_fma_f32 v[26:27], v[42:43], v[8:9], v[26:27] op_sel_hi:[1,0,1] neg_lo:[0,0,1] neg_hi:[0,0,1]
	v_pk_fma_f32 v[50:51], v[60:61], v[60:61], v[50:51]
	v_mul_f32_e32 v64, v61, v61
	v_pk_add_f32 v[50:51], v[64:65], v[50:51] op_sel_hi:[0,1]
	v_pk_fma_f32 v[50:51], v[62:63], v[62:63], v[50:51]
	v_mul_f32_e32 v64, v63, v63
	v_pk_add_f32 v[50:51], v[64:65], v[50:51] op_sel_hi:[0,1]
	v_pk_fma_f32 v[32:33], v[16:17], v[16:17], v[50:51]
	v_pk_mul_f32 v[30:31], v[30:31], v[10:11] op_sel_hi:[1,0]
	v_pk_add_f32 v[32:33], v[34:35], v[32:33] op_sel_hi:[0,1]
	v_pk_fma_f32 v[32:33], v[18:19], v[18:19], v[32:33]
	v_mul_f32_e32 v34, v19, v19
	v_pk_add_f32 v[32:33], v[34:35], v[32:33] op_sel_hi:[0,1]
	v_pk_fma_f32 v[32:33], v[20:21], v[20:21], v[32:33]
	v_mul_f32_e32 v34, v21, v21
	v_pk_add_f32 v[32:33], v[34:35], v[32:33] op_sel_hi:[0,1]
	v_pk_fma_f32 v[32:33], v[22:23], v[22:23], v[32:33]
	v_mul_f32_e32 v34, v23, v23
	v_pk_add_f32 v[32:33], v[34:35], v[32:33] op_sel_hi:[0,1]
	v_pk_fma_f32 v[32:33], v[24:25], v[24:25], v[32:33]
	v_mul_f32_e32 v34, v25, v25
	v_pk_add_f32 v[32:33], v[34:35], v[32:33] op_sel_hi:[0,1]
	v_pk_fma_f32 v[32:33], v[26:27], v[26:27], v[32:33]
	v_mul_f32_e32 v34, v27, v27
	v_pk_mul_f32 v[10:11], v[28:29], v[10:11] op_sel_hi:[1,0]
	v_pk_add_f32 v[32:33], v[34:35], v[32:33] op_sel_hi:[0,1]
	v_pk_fma_f32 v[30:31], v[46:47], v[8:9], v[30:31] op_sel_hi:[1,0,1] neg_lo:[0,0,1] neg_hi:[0,0,1]
	v_pk_fma_f32 v[8:9], v[44:45], v[8:9], v[10:11] op_sel_hi:[1,0,1] neg_lo:[0,0,1] neg_hi:[0,0,1]
	s_waitcnt vmcnt(1)
	v_lshlrev_b32_e32 v12, 16, v90
	v_pk_fma_f32 v[10:11], v[8:9], v[8:9], v[32:33]
	v_mul_f32_e32 v28, v9, v9
	v_pk_add_f32 v[10:11], v[28:29], v[10:11] op_sel_hi:[0,1]
	v_pk_fma_f32 v[10:11], v[30:31], v[30:31], v[10:11]
	v_mul_f32_e32 v28, v31, v31
	v_pk_add_f32 v[10:11], v[28:29], v[10:11] op_sel_hi:[0,1]
	v_mov_b32_e32 v11, v10
	s_nop 1
	v_permlane32_swap_b32_e32 v10, v11
	v_add_f32_e32 v10, v10, v11
	v_fmamk_f32 v10, v10, 0x3c800000, v201
	v_mul_f32_e32 v11, 0x4b800000, v10
	v_cmp_gt_f32_e32 vcc, s87, v10
	v_and_b32_e32 v13, 0xffff0000, v90
	v_lshl_add_u64 v[2:3], v[2:3], 0, v[88:89]
	v_cndmask_b32_e32 v10, v10, v11, vcc
	v_rsq_f32_e32 v28, v10
	v_lshlrev_b32_e32 v10, 16, v91
	v_and_b32_e32 v11, 0xffff0000, v91
	s_mov_b32 s6, 0x120000
	v_mul_f32_e32 v29, 0x45800000, v28
	v_cndmask_b32_e32 v28, v28, v29, vcc
	v_mul_f32_e32 v28, v80, v28
	v_pk_mul_f32 v[32:33], v[48:49], v[28:29] op_sel_hi:[1,0]
	s_waitcnt vmcnt(0)
	v_pk_mul_f32 v[4:5], v[4:5], v[32:33]
	s_nop 0
	v_pk_mul_f32 v[4:5], v[4:5], v[12:13]
	v_pk_mul_f32 v[12:13], v[14:15], v[28:29] op_sel_hi:[1,0]
	v_cvt_pk_bf16_f32 v4, v4, v5
	v_pk_mul_f32 v[6:7], v[6:7], v[12:13]
	v_pk_mul_f32 v[14:15], v[52:53], v[28:29] op_sel_hi:[1,0]
	v_pk_mul_f32 v[6:7], v[6:7], v[10:11]
	s_nop 0
	v_cvt_pk_bf16_f32 v5, v6, v7
	global_store_dwordx2 v[2:3], v[4:5], off
	global_load_dwordx2 v[10:11], v[0:1], off offset:16
	s_nop 0
	global_load_dwordx4 v[4:7], v192, s[4:5] offset:32
	s_waitcnt vmcnt(1)
	v_lshlrev_b32_e32 v12, 16, v10
	v_and_b32_e32 v13, 0xffff0000, v10
	s_waitcnt vmcnt(0)
; DI unsigned pk2(float a, float b) { f2_t v = {a, b}; bf2_t r = __builtin_convertvector(v, bf2_t); return __builtin_bit_cast(unsigned, r); }
; DI float bf2f(bf16_t v) { return __uint_as_float(((unsigned)v) << 16); }
; template <int KIND>
; DI void attn_unit(const Params& p, int l, int b, int head, int qt, int qcol, int kcol, int vfeat, int gcol, int mixcol,
;                   int t1, int n1, int t2, int n2, char* smem) {
;     ...
;         for (int t = 0; t < 2; ++t)
; #pragma unroll
;             for (int q = 0; q < 4; ++q) {
;                 const int f = 32 * t + 8 * q + 4 * h;
;                 const float4 w4 = *(const float4*)(sw + f);
;                 const uint2 gg = *(const uint2*)(grow + f);
;                 const float g0 = bf2f((bf16_t)(gg.x & 0xffff)), g1 = bf2f((bf16_t)(gg.x >> 16)), g2 = bf2f((bf16_t)(gg.y & 0xffff)), g3 = bf2f((bf16_t)(gg.y >> 16));
;                 uint2 o;
;                 o.x = pk2(O0[t][4 * q + 0] * rstd * w4.x * g0, O0[t][4 * q + 1] * rstd * w4.y * g1);
;                 o.y = pk2(O0[t][4 * q + 2] * rstd * w4.z * g2, O0[t][4 * q + 3] * rstd * w4.w * g3);
;                 *(uint2*)(orow + (size_t)t * NTOK * 32 + 8 * q + 4 * h) = o;
;             }
; template <int Q>
; DI void attn_queue(const Params& p, int l, char* smem, int* s_unit, int cb) {
;     ...
;     const int total = (Q == 0) ? (ctxu ? 576 : 512) : (Q == 1) ? (ctxu ? 960 : 768) : 768;
;     for (;;) {
;         if (threadIdx.x == 0) *s_unit = (int)atomicAdd(p.ctr + cb + l * 4 + Q, 1u);
	v_pk_mul_f32 v[4:5], v[4:5], v[14:15]
	v_lshlrev_b32_e32 v10, 16, v11
	v_pk_mul_f32 v[4:5], v[4:5], v[12:13]
	v_pk_mul_f32 v[12:13], v[54:55], v[28:29] op_sel_hi:[1,0]
	v_and_b32_e32 v11, 0xffff0000, v11
	v_pk_mul_f32 v[6:7], v[12:13], v[6:7]
	v_cvt_pk_bf16_f32 v4, v4, v5
	v_pk_mul_f32 v[6:7], v[6:7], v[10:11]
	v_pk_mul_f32 v[14:15], v[56:57], v[28:29] op_sel_hi:[1,0]
	v_cvt_pk_bf16_f32 v5, v6, v7
	global_store_dwordx2 v[2:3], v[4:5], off offset:16
	global_load_dwordx2 v[10:11], v[0:1], off offset:32
	s_nop 0
	global_load_dwordx4 v[4:7], v192, s[4:5] offset:64
	s_waitcnt vmcnt(1)
	v_lshlrev_b32_e32 v12, 16, v10
	v_and_b32_e32 v13, 0xffff0000, v10
	s_waitcnt vmcnt(0)
	v_pk_mul_f32 v[4:5], v[14:15], v[4:5]
	v_lshlrev_b32_e32 v10, 16, v11
	v_pk_mul_f32 v[4:5], v[4:5], v[12:13]
	v_pk_mul_f32 v[12:13], v[58:59], v[28:29] op_sel_hi:[1,0]
	v_and_b32_e32 v11, 0xffff0000, v11
	v_pk_mul_f32 v[6:7], v[12:13], v[6:7]
	v_cvt_pk_bf16_f32 v4, v4, v5
	v_pk_mul_f32 v[6:7], v[6:7], v[10:11]
	v_pk_mul_f32 v[12:13], v[60:61], v[28:29] op_sel_hi:[1,0]
	v_cvt_pk_bf16_f32 v5, v6, v7
	global_store_dwordx2 v[2:3], v[4:5], off offset:32
	global_load_dwordx2 v[10:11], v[0:1], off offset:48
	s_nop 0
	global_load_dwordx4 v[4:7], v192, s[4:5] offset:96
	v_pk_mul_f32 v[14:15], v[62:63], v[28:29] op_sel_hi:[1,0]
	s_waitcnt vmcnt(1)
	v_lshlrev_b32_e32 v32, 16, v10
	v_and_b32_e32 v33, 0xffff0000, v10
	v_lshlrev_b32_e32 v10, 16, v11
	v_and_b32_e32 v11, 0xffff0000, v11
	s_waitcnt vmcnt(0)
	v_pk_mul_f32 v[4:5], v[12:13], v[4:5]
	v_pk_mul_f32 v[6:7], v[14:15], v[6:7]
	v_pk_mul_f32 v[4:5], v[4:5], v[32:33]
	v_pk_mul_f32 v[6:7], v[6:7], v[10:11]
	v_cvt_pk_bf16_f32 v4, v4, v5
	v_cvt_pk_bf16_f32 v5, v6, v7
	global_store_dwordx2 v[2:3], v[4:5], off offset:48
	global_load_dwordx2 v[10:11], v[0:1], off offset:64
	s_nop 0
	global_load_dwordx4 v[4:7], v192, s[4:5] offset:128
	v_add_co_u32_e32 v12, vcc, s6, v2
	v_pk_mul_f32 v[14:15], v[18:19], v[28:29] op_sel_hi:[1,0]
	s_nop 0
	v_addc_co_u32_e32 v13, vcc, 0, v3, vcc
	v_pk_mul_f32 v[2:3], v[16:17], v[28:29] op_sel_hi:[1,0]
	s_waitcnt vmcnt(1)
	v_lshlrev_b32_e32 v16, 16, v10
	v_and_b32_e32 v17, 0xffff0000, v10
	v_lshlrev_b32_e32 v10, 16, v11
	v_and_b32_e32 v11, 0xffff0000, v11
	s_waitcnt vmcnt(0)
	v_pk_mul_f32 v[2:3], v[2:3], v[4:5]
	v_pk_mul_f32 v[4:5], v[14:15], v[6:7]
	v_pk_mul_f32 v[2:3], v[2:3], v[16:17]
	v_pk_mul_f32 v[4:5], v[4:5], v[10:11]
	v_cvt_pk_bf16_f32 v2, v2, v3
	v_cvt_pk_bf16_f32 v3, v4, v5
	global_store_dwordx2 v[12:13], v[2:3], off
	global_load_dwordx2 v[6:7], v[0:1], off offset:80
	s_nop 0
	global_load_dwordx4 v[2:5], v192, s[4:5] offset:160
	v_pk_mul_f32 v[10:11], v[20:21], v[28:29] op_sel_hi:[1,0]
	v_pk_mul_f32 v[14:15], v[22:23], v[28:29] op_sel_hi:[1,0]
	s_waitcnt vmcnt(1)
	v_lshlrev_b32_e32 v16, 16, v6
	v_and_b32_e32 v17, 0xffff0000, v6
	v_lshlrev_b32_e32 v6, 16, v7
	v_and_b32_e32 v7, 0xffff0000, v7
	s_waitcnt vmcnt(0)
	v_pk_mul_f32 v[2:3], v[10:11], v[2:3]
	v_pk_mul_f32 v[4:5], v[14:15], v[4:5]
	v_pk_mul_f32 v[2:3], v[2:3], v[16:17]
	v_pk_mul_f32 v[4:5], v[4:5], v[6:7]
	v_cvt_pk_bf16_f32 v2, v2, v3
	v_cvt_pk_bf16_f32 v3, v4, v5
	global_store_dwordx2 v[12:13], v[2:3], off offset:16
	global_load_dwordx2 v[6:7], v[0:1], off offset:96
	s_nop 0
	global_load_dwordx4 v[2:5], v192, s[4:5] offset:192
	v_pk_mul_f32 v[10:11], v[24:25], v[28:29] op_sel_hi:[1,0]
	v_pk_mul_f32 v[14:15], v[26:27], v[28:29] op_sel_hi:[1,0]
	s_waitcnt vmcnt(1)
	v_lshlrev_b32_e32 v16, 16, v6
	v_and_b32_e32 v17, 0xffff0000, v6
	v_lshlrev_b32_e32 v6, 16, v7
	v_and_b32_e32 v7, 0xffff0000, v7
	s_waitcnt vmcnt(0)
	v_pk_mul_f32 v[2:3], v[10:11], v[2:3]
	v_pk_mul_f32 v[4:5], v[14:15], v[4:5]
	v_pk_mul_f32 v[2:3], v[2:3], v[16:17]
	v_pk_mul_f32 v[4:5], v[4:5], v[6:7]
	v_cvt_pk_bf16_f32 v2, v2, v3
	v_cvt_pk_bf16_f32 v3, v4, v5
	global_store_dwordx2 v[12:13], v[2:3], off offset:32
	global_load_dwordx2 v[4:5], v[0:1], off offset:112
	s_nop 0
	global_load_dwordx4 v[0:3], v192, s[4:5] offset:224
	v_pk_mul_f32 v[6:7], v[8:9], v[28:29] op_sel_hi:[1,0]
	v_pk_mul_f32 v[8:9], v[30:31], v[28:29] op_sel_hi:[1,0]
	s_mov_b64 s[4:5], 0
	s_waitcnt vmcnt(1)
	v_lshlrev_b32_e32 v10, 16, v4
	v_and_b32_e32 v11, 0xffff0000, v4
	v_lshlrev_b32_e32 v4, 16, v5
	v_and_b32_e32 v5, 0xffff0000, v5
	s_waitcnt vmcnt(0)
	v_pk_mul_f32 v[0:1], v[6:7], v[0:1]
	v_pk_mul_f32 v[2:3], v[8:9], v[2:3]
	v_pk_mul_f32 v[0:1], v[0:1], v[10:11]
	v_pk_mul_f32 v[2:3], v[2:3], v[4:5]
	v_cvt_pk_bf16_f32 v0, v0, v1
	v_cvt_pk_bf16_f32 v1, v2, v3
	global_store_dwordx2 v[12:13], v[0:1], off offset:48
	s_branch .LBB0_71
.LBB0_84:
	s_and_b64 s[4:5], s[44:45], exec
	s_movk_i32 s4, 0x3c0
	s_cselect_b32 s28, s4, 0x300
	s_movk_i32 s61, 0x800
	s_and_saveexec_b64 s[4:5], s[54:55]
	s_cbranch_execz .Ltk_e1
	s_load_dwordx2 s[100:101], s[0:1], 0x100
	s_lshl_b32 m0, s48, 2
	v_mov_b32_e32 v253, 1
	s_waitcnt lgkmcnt(0)
	s_add_u32 s100, s100, m0
	s_addc_u32 s101, s101, 0
	global_atomic_add v253, v193, v253, s[100:101] offset:4 sc0

; template <int Q>
; DI void attn_queue(const Params& p, int l, char* smem, int* s_unit, int cb) {
;     ...
;     for (;;) {
;         if (threadIdx.x == 0) *s_unit = (int)atomicAdd(p.ctr + cb + l * 4 + Q, 1u);
.Ltk_q2pre:
	s_and_saveexec_b64 s[4:5], s[54:55]
	s_cbranch_execz .Ltk_e2
	s_load_dwordx2 s[100:101], s[0:1], 0x100
	s_lshl_b32 m0, s48, 2
	v_mov_b32_e32 v253, 1
	s_waitcnt lgkmcnt(0)
	s_add_u32 s100, s100, m0
	s_addc_u32 s101, s101, 0
	global_atomic_add v253, v193, v253, s[100:101] offset:8 sc0

; template <int KIND>
; DI void attn_unit(const Params& p, int l, int b, int head, int qt, int qcol, int kcol, int vfeat, int gcol, int mixcol,
;                   int t1, int n1, int t2, int n2, char* smem) {
;     ...
;     for (int it = 0; it < nt; ++it) {
;         const int tile = (it < n1) ? t1 + it : t2 + (it - n1);
;         if (it + 1 < nt) asm volatile("s_waitcnt vmcnt(4)" ::: "memory"); else asm volatile("s_waitcnt vmcnt(0)" ::: "memory");
;         __builtin_amdgcn_s_barrier();
;         const char* sk = smem + sc * ATT_SLOT;
;         const char* sv = sk + ATT_V;
;         bool active = true;
;         if (KIND == 2 && tile < 32) active = (tile >= r0w) && (tile < r0w + 8);
;         bf16x8 kf[8], vf[8];
;         if (active) {
; #pragma unroll
;             for (int s = 0; s < 4; ++s)
; #pragma unroll
;                 for (int t = 0; t < 2; ++t) kf[2 * s + t] = *(const bf16x8*)(sk + (32 * t + r) * 128 + (((2 * s + h) ^ xr) << 4));
;         }
;         __builtin_amdgcn_sched_barrier(0);
;         if (it + 2 < nt) { const int nx = (it + 2 < n1) ? t1 + it + 2 : t2 + (it + 2 - n1); KV_ISSUE(nx, sn); }
;         sc = (sc == 2) ? 0 : sc + 1; sn = (sn == 2) ? 0 : sn + 1;
;         __builtin_amdgcn_sched_barrier(0);
;         if (active) {
;     ...
;             if (KIND == 0) {
;                 f32x16 S0[2], S1[2];
; #pragma unroll
;                 for (int t = 0; t < 2; ++t) { S0[t] = MFMA(kf[t], qf[0], cz); S1[t] = MFMA(kf[4 + t], qf[2], cz); }
; #pragma unroll
;                 for (int t = 0; t < 2; ++t) { S0[t] = MFMA(kf[2 + t], qf[1], S0[t]); S1[t] = MFMA(kf[6 + t], qf[3], S1[t]); }
;                 LOAD_VF();
;                 softmax_tile(S0, l0);
;                 pv_tile(S0, O0, vf);
;                 softmax_tile(S1, l1);
;                 pv_tile(S1, O1, vf);
;             } else {
;                 f32x16 S[2];
; #pragma unroll
;                 for (int t = 0; t < 2; ++t) S[t] = MFMA(kf[t], qf[0], cz);
; #pragma unroll
;                 for (int s = 1; s < 4; ++s)
; #pragma unroll
;                     for (int t = 0; t < 2; ++t) S[t] = MFMA(kf[2 * s + t], qf[s], S[t]);
;                 LOAD_VF();
;                 if (KIND == 2 && tile < 32) {
;                     const char* brow = smem + ATT_BIAS + (tile - nrow + 7) * 128;
; #pragma unroll
;                     for (int t = 0; t < 2; ++t)
; #pragma unroll
.Lk1_drain:
	s_mov_b32 s35, s34
	v_exp_f32_e32 v238, v56
	v_exp_f32_e32 v239, v57
	v_exp_f32_e32 v240, v58
	v_exp_f32_e32 v241, v59
	v_exp_f32_e32 v242, v60
	v_exp_f32_e32 v243, v61
	v_exp_f32_e32 v244, v62
	v_exp_f32_e32 v245, v63
	v_cvt_pk_bf16_f32 v176, v214, v215
	v_cvt_pk_bf16_f32 v177, v216, v217
	v_add_f32_e32 v199, v214, v216
	v_add_f32_e32 v192, v215, v217
	v_add_f32_e32 v199, v218, v199
	v_add_f32_e32 v192, v219, v192
	v_cvt_pk_bf16_f32 v178, v218, v219
	v_cvt_pk_bf16_f32 v179, v220, v221
	v_add_f32_e32 v199, v220, v199
	v_add_f32_e32 v192, v221, v192
	v_add_f32_e32 v199, v222, v199
	v_add_f32_e32 v192, v223, v192
	v_cvt_pk_bf16_f32 v180, v222, v223
	v_cvt_pk_bf16_f32 v181, v224, v225
	v_add_f32_e32 v199, v224, v199
	v_add_f32_e32 v192, v225, v192
	v_add_f32_e32 v199, v226, v199
	v_add_f32_e32 v192, v227, v192
	v_cvt_pk_bf16_f32 v182, v226, v227
	v_cvt_pk_bf16_f32 v183, v228, v229
	v_add_f32_e32 v199, v228, v199
	v_add_f32_e32 v192, v229, v192
	v_add_f32_e32 v199, v230, v199
	v_add_f32_e32 v192, v231, v192
	v_cvt_pk_bf16_f32 v184, v230, v231
	v_cvt_pk_bf16_f32 v185, v232, v233
	v_add_f32_e32 v199, v232, v199
	v_add_f32_e32 v192, v233, v192
	v_add_f32_e32 v199, v234, v199
	v_add_f32_e32 v192, v235, v192
	v_cvt_pk_bf16_f32 v186, v234, v235
	v_cvt_pk_bf16_f32 v187, v236, v237
	v_add_f32_e32 v199, v236, v199
	v_add_f32_e32 v192, v237, v192
	v_add_f32_e32 v199, v238, v199
	v_add_f32_e32 v192, v239, v192
	v_cvt_pk_bf16_f32 v188, v238, v239
	v_cvt_pk_bf16_f32 v189, v240, v241
	v_add_f32_e32 v199, v240, v199
	v_add_f32_e32 v192, v241, v192
	v_add_f32_e32 v199, v242, v199
	v_add_f32_e32 v192, v243, v192
	v_cvt_pk_bf16_f32 v190, v242, v243
	v_cvt_pk_bf16_f32 v191, v244, v245
	v_add_f32_e32 v199, v244, v199
	v_add_f32_e32 v192, v245, v192
	v_add_f32_e32 v199, v199, v192
	v_add_f32_e32 v104, v104, v199
	s_waitcnt lgkmcnt(0)
	v_mfma_f32_32x32x16_bf16 v[32:47], v[110:113], v[176:179], v[32:47]
	v_mfma_f32_32x32x16_bf16 v[0:15], v[114:117], v[176:179], v[0:15]
	v_mfma_f32_32x32x16_bf16 v[32:47], v[118:121], v[180:183], v[32:47]
	v_mfma_f32_32x32x16_bf16 v[0:15], v[122:125], v[180:183], v[0:15]
	v_mfma_f32_32x32x16_bf16 v[32:47], v[126:129], v[184:187], v[32:47]
	v_mfma_f32_32x32x16_bf16 v[0:15], v[130:133], v[184:187], v[0:15]
	v_mfma_f32_32x32x16_bf16 v[32:47], v[134:137], v[188:191], v[32:47]
	v_mfma_f32_32x32x16_bf16 v[0:15], v[138:141], v[188:191], v[0:15]
	s_lshl_b32 s4, s35, 14
	s_add_i32 s5, s4, 32
	v_add_u32_e32 v52, s5, v105
	v_add_u32_e32 v100, v52, v107
	v_add_u32_e32 v132, v52, v106
	v_add_u32_e32 v133, v52, v103
	v_add_u32_e32 v134, v52, v101
	s_waitcnt vmcnt(4)
	s_barrier
	ds_read_b128 v[48:51], v100
	ds_read_b128 v[96:99], v100 offset:4096
	ds_read_b128 v[108:111], v132
	ds_read_b128 v[112:115], v132 offset:4096
	ds_read_b128 v[116:119], v133
	ds_read_b128 v[120:123], v133 offset:4096
	ds_read_b128 v[124:127], v134
	ds_read_b128 v[128:131], v134 offset:4096
	s_waitcnt lgkmcnt(0)
	v_mfma_f32_32x32x16_bf16 v[64:79], v[48:51], v[92:95], v[16:31]
	v_mfma_f32_32x32x16_bf16 v[48:63], v[96:99], v[92:95], v[16:31]
	v_mfma_f32_32x32x16_bf16 v[64:79], v[108:111], v[88:91], v[64:79]
	v_mfma_f32_32x32x16_bf16 v[48:63], v[112:115], v[88:91], v[48:63]
	v_mfma_f32_32x32x16_bf16 v[64:79], v[116:119], v[84:87], v[64:79]
	v_mfma_f32_32x32x16_bf16 v[48:63], v[120:123], v[84:87], v[48:63]
	v_mfma_f32_32x32x16_bf16 v[64:79], v[124:127], v[80:83], v[64:79]
	v_mfma_f32_32x32x16_bf16 v[48:63], v[128:131], v[80:83], v[48:63]
	ds_read_b128 v[96:99], v100 offset:8192
	ds_read_b128 v[108:111], v100 offset:12288
	ds_read_b128 v[112:115], v132 offset:8192
	ds_read_b128 v[116:119], v132 offset:12288
	ds_read_b128 v[120:123], v133 offset:8192
	ds_read_b128 v[124:127], v133 offset:12288
	ds_read_b128 v[128:131], v134 offset:8192
	ds_read_b128 v[132:135], v134 offset:12288
	s_nop 2
	v_exp_f32_e32 v64, v64
	v_exp_f32_e32 v65, v65
	v_exp_f32_e32 v66, v66
	v_exp_f32_e32 v67, v67
	v_exp_f32_e32 v68, v68
	v_exp_f32_e32 v69, v69
	v_exp_f32_e32 v70, v70
	v_exp_f32_e32 v71, v71
	v_add_f32_e64 v136, v64, 0
	v_add_f32_e64 v137, v65, 0
	v_exp_f32_e32 v72, v72
	v_add_f32_e64 v136, v66, v136
	v_add_f32_e64 v137, v67, v137
	v_exp_f32_e32 v73, v73
	v_cvt_pk_bf16_f32 v64, v64, v65
	v_cvt_pk_bf16_f32 v65, v66, v67
	v_cvt_pk_bf16_f32 v66, v68, v69
	v_cvt_pk_bf16_f32 v67, v70, v71
	v_exp_f32_e32 v74, v74
	v_exp_f32_e32 v75, v75
	s_waitcnt lgkmcnt(0)
	v_mfma_f32_32x32x16_bf16 v[32:47], v[96:99], v[64:67], v[32:47]
	v_add_f32_e64 v136, v68, v136
	v_add_f32_e64 v137, v69, v137
	v_exp_f32_e32 v68, v76
	v_exp_f32_e32 v69, v77
	v_add_f32_e64 v136, v70, v136
	v_add_f32_e64 v137, v71, v137
	v_exp_f32_e32 v70, v78
	v_exp_f32_e32 v71, v79
	v_add_f32_e64 v136, v72, v136
	v_add_f32_e64 v137, v73, v137
	v_mfma_f32_32x32x16_bf16 v[0:15], v[108:111], v[64:67], v[0:15]
	v_exp_f32_e32 v48, v48
	v_exp_f32_e32 v49, v49
	v_add_f32_e64 v136, v74, v136
	v_add_f32_e64 v137, v75, v137
	v_exp_f32_e32 v50, v50
	v_add_f32_e64 v76, v68, v136
	v_add_f32_e64 v77, v69, v137
	v_cvt_pk_bf16_f32 v66, v68, v69
	v_add_f32_e64 v64, v70, v76
	v_add_f32_e64 v65, v71, v77
	v_cvt_pk_bf16_f32 v67, v70, v71
	v_add_f32_e64 v76, v48, v64
	v_add_f32_e64 v77, v49, v65
	v_cvt_pk_bf16_f32 v64, v72, v73
	v_cvt_pk_bf16_f32 v65, v74, v75
	v_exp_f32_e32 v51, v51
	v_exp_f32_e32 v52, v52
	v_mfma_f32_32x32x16_bf16 v[32:47], v[112:115], v[64:67], v[32:47]
	v_exp_f32_e32 v53, v53
	v_exp_f32_e32 v54, v54
	v_exp_f32_e32 v55, v55
	v_add_f32_e64 v68, v50, v76
	v_add_f32_e64 v69, v51, v77
	v_exp_f32_e32 v56, v56
	v_add_f32_e64 v68, v52, v68
	v_add_f32_e64 v69, v53, v69
	v_exp_f32_e32 v57, v57
	v_mfma_f32_32x32x16_bf16 v[0:15], v[116:119], v[64:67], v[0:15]
	v_add_f32_e64 v64, v54, v68
	v_add_f32_e64 v65, v55, v69
	v_cvt_pk_bf16_f32 v48, v48, v49
	v_cvt_pk_bf16_f32 v49, v50, v51
	v_cvt_pk_bf16_f32 v51, v54, v55
	v_exp_f32_e32 v54, v58
	v_exp_f32_e32 v55, v59
	s_addk_i32 s4, 0x4000
	s_cmp_lg_u32 s35, 2
	v_cvt_pk_bf16_f32 v50, v52, v53
	s_cselect_b32 s4, s4, 0
	v_add_f32_e64 v52, v56, v64
	v_add_f32_e64 v53, v57, v65
	v_mfma_f32_32x32x16_bf16 v[32:47], v[120:123], v[48:51], v[32:47]
	s_add_i32 s4, s4, 32
	v_exp_f32_e32 v58, v60
	v_exp_f32_e32 v59, v61
	v_exp_f32_e32 v60, v62
	v_exp_f32_e32 v61, v63
	s_waitcnt vmcnt(0)
	s_barrier
; template <int KIND>
; DI void attn_unit(const Params& p, int l, int b, int head, int qt, int qcol, int kcol, int vfeat, int gcol, int mixcol,
;                   int t1, int n1, int t2, int n2, char* smem) {
;     ...
;         bf16x8 kf[8], vf[8];
;         if (active) {
; #pragma unroll
;             for (int s = 0; s < 4; ++s)
; #pragma unroll
;                 for (int t = 0; t < 2; ++t) kf[2 * s + t] = *(const bf16x8*)(sk + (32 * t + r) * 128 + (((2 * s + h) ^ xr) << 4));
;         }
;         __builtin_amdgcn_sched_barrier(0);
;         if (it + 2 < nt) { const int nx = (it + 2 < n1) ? t1 + it + 2 : t2 + (it + 2 - n1); KV_ISSUE(nx, sn); }
;         sc = (sc == 2) ? 0 : sc + 1; sn = (sn == 2) ? 0 : sn + 1;
;         __builtin_amdgcn_sched_barrier(0);
;         if (active) {
;     ...
;             if (KIND == 0) {
;                 f32x16 S0[2], S1[2];
; #pragma unroll
;                 for (int t = 0; t < 2; ++t) { S0[t] = MFMA(kf[t], qf[0], cz); S1[t] = MFMA(kf[4 + t], qf[2], cz); }
; #pragma unroll
;                 for (int t = 0; t < 2; ++t) { S0[t] = MFMA(kf[2 + t], qf[1], S0[t]); S1[t] = MFMA(kf[6 + t], qf[3], S1[t]); }
;                 LOAD_VF();
;                 softmax_tile(S0, l0);
;                 pv_tile(S0, O0, vf);
;                 softmax_tile(S1, l1);
;                 pv_tile(S1, O1, vf);
;             } else {
;                 f32x16 S[2];
; #pragma unroll
;                 for (int t = 0; t < 2; ++t) S[t] = MFMA(kf[t], qf[0], cz);
; #pragma unroll
;                 for (int s = 1; s < 4; ++s)
; #pragma unroll
;                     for (int t = 0; t < 2; ++t) S[t] = MFMA(kf[2 * s + t], qf[s], S[t]);
;                 LOAD_VF();
;                 if (KIND == 2 && tile < 32) {
;                     const char* brow = smem + ATT_BIAS + (tile - nrow + 7) * 128;
; #pragma unroll
;                     for (int t = 0; t < 2; ++t)
; #pragma unroll
;                         for (int e = 0; e < 16; ++e) S[t][e] += *(const float*)(brow + bcol[t][e]);
;                 }
;                 softmax_tile(S, l0);
;                 pv_tile(S, O0, vf);
;             }
;     ...
;         }
;     }
;     l0 = xsum32(l0);
;     const float inv0 = 1.f / l0;
;     const int tid_e = otid();
;     const size_t qrow_e = (size_t)b * TPB + qt * 128 + 32 * (tid_e >> 6) + (tid_e & 31);
;     bf16_t* orow = p.hmix + ((size_t)(mixcol >> 5) * NTOK + qrow_e) * 32;
	s_mov_b64 exec, s[54:55]
	s_load_dwordx2 s[100:101], s[0:1], 0x100
	s_lshl_b32 m0, s48, 2
	v_mov_b32_e32 v253, 1
	s_waitcnt lgkmcnt(0)
	s_add_u32 s100, s100, m0
	s_addc_u32 s101, s101, 0
	global_atomic_add v253, v193, v253, s[100:101] offset:4 sc0
	s_mov_b64 exec, -1
	v_mfma_f32_32x32x16_bf16 v[0:15], v[124:127], v[48:51], v[0:15]
	v_add_f32_e64 v48, v54, v52
	v_add_f32_e64 v49, v55, v53
	v_add_u32_e32 v52, s4, v105
	v_add_u32_e32 v105, v52, v107
	v_add_u32_e32 v118, v52, v106
	v_add_u32_e32 v103, v52, v103
	v_add_u32_e32 v119, v52, v101
	ds_read_b128 v[64:67], v105
	ds_read_b128 v[68:71], v105 offset:4096
	ds_read_b128 v[72:75], v118
	ds_read_b128 v[76:79], v118 offset:4096
	ds_read_b128 v[106:109], v103
	ds_read_b128 v[110:113], v103 offset:4096
	ds_read_b128 v[98:101], v119
	ds_read_b128 v[114:117], v119 offset:4096
	v_add_f32_e64 v48, v58, v48
	v_add_f32_e64 v49, v59, v49
	v_cvt_pk_bf16_f32 v50, v58, v59
	v_add_f32_e64 v96, v60, v48
	v_add_f32_e64 v97, v61, v49
	v_cvt_pk_bf16_f32 v48, v56, v57
	v_cvt_pk_bf16_f32 v49, v54, v55
	v_cvt_pk_bf16_f32 v51, v60, v61
	s_nop 1
	v_mfma_f32_32x32x16_bf16 v[32:47], v[128:131], v[48:51], v[32:47]
	v_mfma_f32_32x32x16_bf16 v[0:15], v[132:135], v[48:51], v[0:15]
	s_waitcnt lgkmcnt(0)
	v_mfma_f32_32x32x16_bf16 v[48:63], v[64:67], v[92:95], v[16:31]
	v_mfma_f32_32x32x16_bf16 v[16:31], v[68:71], v[92:95], v[16:31]
	v_mfma_f32_32x32x16_bf16 v[48:63], v[72:75], v[88:91], v[48:63]
	v_mfma_f32_32x32x16_bf16 v[16:31], v[76:79], v[88:91], v[16:31]
	v_mfma_f32_32x32x16_bf16 v[48:63], v[106:109], v[84:87], v[48:63]
	v_mfma_f32_32x32x16_bf16 v[16:31], v[110:113], v[84:87], v[16:31]
	v_mfma_f32_32x32x16_bf16 v[48:63], v[98:101], v[80:83], v[48:63]
	v_mfma_f32_32x32x16_bf16 v[16:31], v[114:117], v[80:83], v[16:31]
	ds_read_b128 v[92:95], v105 offset:8192
	ds_read_b128 v[76:79], v105 offset:12288
	ds_read_b128 v[88:91], v118 offset:8192
	ds_read_b128 v[72:75], v118 offset:12288
	ds_read_b128 v[84:87], v103 offset:8192
	ds_read_b128 v[68:71], v103 offset:12288
	ds_read_b128 v[80:83], v119 offset:8192
	ds_read_b128 v[64:67], v119 offset:12288
	s_nop 2
	v_exp_f32_e32 v98, v48
	v_exp_f32_e32 v99, v49
	v_exp_f32_e32 v50, v50
	v_exp_f32_e32 v51, v51
	v_exp_f32_e32 v52, v52
	v_exp_f32_e32 v53, v53
	v_exp_f32_e32 v54, v54
	v_exp_f32_e32 v55, v55
	v_add_f32_e64 v48, v98, 0
	v_add_f32_e64 v49, v99, 0
	v_exp_f32_e32 v56, v56
	v_exp_f32_e32 v57, v57
	v_add_f32_e64 v48, v50, v48
	v_add_f32_e64 v49, v51, v49
	v_mov_b32_e32 v103, v200
	v_add_f32_e64 v48, v52, v48
	v_add_f32_e64 v49, v53, v49
	s_add_u32 s4, s29, s6
	v_add_f32_e64 v48, v54, v48
	v_add_f32_e64 v49, v55, v49
	s_addc_u32 s5, s7, 0
	v_add_f32_e64 v100, v56, v48
	v_add_f32_e64 v101, v57, v49
	v_ashrrev_i32_e32 v48, 1, v103
	v_and_b32_e32 v48, 0xffffffe0, v48
	v_ashrrev_i32_e32 v49, 31, v48
	v_and_or_b32 v106, v103, 31, s4
	v_mov_b32_e32 v107, s5
	s_lshr_b32 s4, s9, 6
	v_lshl_add_u64 v[106:107], v[106:107], 0, v[48:49]
	s_mulk_i32 s4, 0x4800
	s_mov_b32 s5, s75
	v_lshl_add_u64 v[48:49], v[106:107], 0, s[4:5]
	v_lshlrev_b64 v[48:49], 7, v[48:49]
	v_lshl_add_u64 v[48:49], s[40:41], 0, v[48:49]
	v_lshlrev_b32_e32 v192, 3, v102
	v_lshl_add_u64 v[48:49], v[48:49], 0, v[192:193]
	global_load_dwordx2 v[102:103], v[48:49], off
	v_exp_f32_e32 v58, v58
	v_exp_f32_e32 v59, v59
	v_exp_f32_e32 v60, v60
	v_exp_f32_e32 v61, v61
	v_exp_f32_e32 v62, v62
	v_exp_f32_e32 v63, v63
	v_exp_f32_e32 v114, v28
	v_exp_f32_e32 v115, v29
	v_exp_f32_e32 v116, v30
	v_exp_f32_e32 v117, v31
	v_cvt_pk_bf16_f32 v28, v98, v99
	v_cvt_pk_bf16_f32 v29, v50, v51
	v_cvt_pk_bf16_f32 v30, v52, v53
	v_cvt_pk_bf16_f32 v31, v54, v55
	v_exp_f32_e32 v16, v16
	v_exp_f32_e32 v17, v17
	s_waitcnt lgkmcnt(0)
	v_mfma_f32_32x32x16_bf16 v[32:47], v[92:95], v[28:31], v[32:47]
	v_add_f32_e64 v100, v58, v100
	v_add_f32_e64 v101, v59, v101
	v_exp_f32_e32 v18, v18
	v_exp_f32_e32 v19, v19
	v_add_f32_e64 v100, v60, v100
	v_add_f32_e64 v101, v61, v101
	v_exp_f32_e32 v108, v20
	v_exp_f32_e32 v109, v21
	v_add_f32_e64 v100, v62, v100
	v_add_f32_e64 v101, v63, v101
	v_exp_f32_e32 v110, v22
	v_exp_f32_e32 v111, v23
	v_add_f32_e64 v20, v16, v100
	v_add_f32_e64 v21, v17, v101
	v_exp_f32_e32 v100, v24
	v_exp_f32_e32 v101, v25
	v_add_f32_e64 v20, v18, v20
	v_add_f32_e64 v21, v19, v21
	v_exp_f32_e32 v112, v26
	v_exp_f32_e32 v113, v27
	v_add_f32_e64 v20, v108, v20
	v_add_f32_e64 v21, v109, v21
	v_cvt_pk_bf16_f32 v24, v56, v57
	v_add_f32_e64 v20, v110, v20
	v_add_f32_e64 v21, v111, v21
	v_cvt_pk_bf16_f32 v25, v58, v59
	v_cvt_pk_bf16_f32 v26, v60, v61
	v_cvt_pk_bf16_f32 v27, v62, v63
	v_add_f32_e64 v20, v100, v20
	v_add_f32_e64 v21, v101, v21
	v_mov_b32_e32 v22, v96
	v_mfma_f32_32x32x16_bf16 v[32:47], v[88:91], v[24:27], v[32:47]
	v_add_f32_e64 v20, v112, v20
	v_add_f32_e64 v21, v113, v21
	s_lshr_b32 s6, s8, 5
	v_add_f32_e64 v20, v114, v20
	v_add_f32_e64 v21, v115, v21
	s_mulk_i32 s6, 0x4800
	v_add_f32_e64 v20, v116, v20
	v_add_f32_e64 v21, v117, v21
	s_ashr_i32 s7, s6, 31
	v_mov_b32_e32 v23, v20
	v_mov_b32_e32 v20, v97
	v_add_f32_e64 v20, v22, v20
	v_add_f32_e64 v21, v23, v21
	v_cvt_pk_bf16_f32 v22, v108, v109
	v_add_f32_e32 v20, v104, v20
	v_add_f32_e32 v50, v20, v21
	v_cvt_pk_bf16_f32 v20, v16, v17
	v_cvt_pk_bf16_f32 v21, v18, v19
	v_cvt_pk_bf16_f32 v23, v110, v111
	v_mov_b32_e32 v18, v50
	s_nop 1
	v_permlane32_swap_b32_e32 v50, v18
	v_mfma_f32_32x32x16_bf16 v[32:47], v[84:87], v[20:23], v[32:47]
	v_add_f32_e32 v50, v50, v18
	v_div_scale_f32 v51, s[4:5], v50, v50, 1.0
	v_rcp_f32_e32 v52, v51
	v_cvt_pk_bf16_f32 v16, v100, v101
	v_cvt_pk_bf16_f32 v17, v112, v113
	v_cvt_pk_bf16_f32 v18, v114, v115
	v_cvt_pk_bf16_f32 v19, v116, v117
	v_fma_f32 v53, -v51, v52, 1.0
	v_fmac_f32_e32 v52, v53, v52
	v_mfma_f32_32x32x16_bf16 v[32:47], v[80:83], v[16:19], v[32:47]
	v_div_scale_f32 v53, vcc, 1.0, v50, 1.0
	v_mul_f32_e32 v54, v53, v52
	v_fma_f32 v55, -v51, v54, v53
	v_fmac_f32_e32 v54, v55, v52
	s_load_dwordx2 s[4:5], s[0:1], 0xb8
	v_fma_f32 v51, -v51, v54, v53
	v_div_fmas_f32 v51, v51, v52, v54
	v_div_fixup_f32 v50, v51, v50, 1.0
	v_lshl_add_u64 v[52:53], v[106:107], 0, s[6:7]
	v_lshlrev_b64 v[52:53], 6, v[52:53]
	s_waitcnt vmcnt(0)
; DI unsigned pk2(float a, float b) { f2_t v = {a, b}; bf2_t r = __builtin_convertvector(v, bf2_t); return __builtin_bit_cast(unsigned, r); }
; DI float bf2f(bf16_t v) { return __uint_as_float(((unsigned)v) << 16); }
; template <int KIND>
; DI void attn_unit(const Params& p, int l, int b, int head, int qt, int qcol, int kcol, int vfeat, int gcol, int mixcol,
;                   int t1, int n1, int t2, int n2, char* smem) {
;     ...
;     } else {
; #pragma unroll
;         for (int t = 0; t < 2; ++t)
; #pragma unroll
;             for (int q = 0; q < 4; ++q) {
;                 const int f = 32 * t + 8 * q + 4 * h;
;                 const uint2 gg = *(const uint2*)(grow + f);
;                 const float g0 = bf2f((bf16_t)(gg.x & 0xffff)), g1 = bf2f((bf16_t)(gg.x >> 16)), g2 = bf2f((bf16_t)(gg.y & 0xffff)), g3 = bf2f((bf16_t)(gg.y >> 16));
;                 uint2 o;
;                 o.x = pk2(O0[t][4 * q + 0] * inv0 * g0, O0[t][4 * q + 1] * inv0 * g1);
;                 o.y = pk2(O0[t][4 * q + 2] * inv0 * g2, O0[t][4 * q + 3] * inv0 * g3);
;                 *(uint2*)(orow + (size_t)t * NTOK * 32 + 8 * q + 4 * h) = o;
;             }
	v_lshlrev_b32_e32 v54, 16, v102
	v_and_b32_e32 v55, 0xffff0000, v102
	v_lshlrev_b32_e32 v56, 16, v103
	v_and_b32_e32 v57, 0xffff0000, v103
	v_pk_mul_f32 v[32:33], v[32:33], v[50:51] op_sel_hi:[1,0]
	v_pk_mul_f32 v[34:35], v[34:35], v[50:51] op_sel_hi:[1,0]
	s_waitcnt lgkmcnt(0)
	v_lshl_add_u64 v[52:53], s[4:5], 0, v[52:53]
	v_pk_mul_f32 v[32:33], v[32:33], v[54:55]
	v_pk_mul_f32 v[34:35], v[34:35], v[56:57]
	v_lshl_add_u64 v[52:53], v[52:53], 0, v[192:193]
	v_cvt_pk_bf16_f32 v32, v32, v33
	v_cvt_pk_bf16_f32 v33, v34, v35
	global_store_dwordx2 v[52:53], v[32:33], off
	global_load_dwordx2 v[32:33], v[48:49], off offset:16
	v_mfma_f32_32x32x16_bf16 v[0:15], v[76:79], v[28:31], v[0:15]
	v_mul_f32_e64 v28, v36, v50
	v_mul_f32_e64 v29, v37, v50
	v_mul_f32_e64 v30, v38, v50
	v_mul_f32_e64 v31, v39, v50
	s_mov_b32 s4, 0x120000
	s_waitcnt vmcnt(0)
	v_lshlrev_b32_e32 v34, 16, v32
	v_and_b32_e32 v35, 0xffff0000, v32
	v_lshlrev_b32_e32 v32, 16, v33
	v_and_b32_e32 v33, 0xffff0000, v33
	v_pk_mul_f32 v[28:29], v[28:29], v[34:35]
	v_pk_mul_f32 v[30:31], v[30:31], v[32:33]
	v_cvt_pk_bf16_f32 v28, v28, v29
	v_cvt_pk_bf16_f32 v29, v30, v31
	global_store_dwordx2 v[52:53], v[28:29], off offset:16
	global_load_dwordx2 v[28:29], v[48:49], off offset:32
	v_mfma_f32_32x32x16_bf16 v[0:15], v[72:75], v[24:27], v[0:15]
	v_mul_f32_e64 v24, v40, v50
	v_mul_f32_e64 v25, v41, v50
	v_mul_f32_e64 v26, v42, v50
	v_mul_f32_e64 v27, v43, v50
	s_waitcnt vmcnt(0)
	v_lshlrev_b32_e32 v30, 16, v28
	v_and_b32_e32 v31, 0xffff0000, v28
	v_lshlrev_b32_e32 v28, 16, v29
	v_and_b32_e32 v29, 0xffff0000, v29
	v_pk_mul_f32 v[24:25], v[24:25], v[30:31]
	v_pk_mul_f32 v[26:27], v[26:27], v[28:29]
	v_cvt_pk_bf16_f32 v24, v24, v25
	v_cvt_pk_bf16_f32 v25, v26, v27
	global_store_dwordx2 v[52:53], v[24:25], off offset:32
	global_load_dwordx2 v[24:25], v[48:49], off offset:48
	v_mfma_f32_32x32x16_bf16 v[0:15], v[68:71], v[20:23], v[0:15]
	v_mul_f32_e64 v20, v44, v50
	v_mul_f32_e64 v21, v45, v50
	v_mul_f32_e64 v22, v46, v50
	v_mul_f32_e64 v23, v47, v50
	s_waitcnt vmcnt(0)
	v_lshlrev_b32_e32 v26, 16, v24
	v_and_b32_e32 v27, 0xffff0000, v24
	v_lshlrev_b32_e32 v24, 16, v25
	v_and_b32_e32 v25, 0xffff0000, v25
	v_pk_mul_f32 v[20:21], v[20:21], v[26:27]
	v_pk_mul_f32 v[22:23], v[22:23], v[24:25]
	v_cvt_pk_bf16_f32 v20, v20, v21
	v_cvt_pk_bf16_f32 v21, v22, v23
	global_store_dwordx2 v[52:53], v[20:21], off offset:48
	global_load_dwordx2 v[20:21], v[48:49], off offset:64
	v_mfma_f32_32x32x16_bf16 v[0:15], v[64:67], v[16:19], v[0:15]
	v_add_co_u32_e32 v22, vcc, s4, v52
	s_mov_b64 s[4:5], 0
	s_nop 0
	v_addc_co_u32_e32 v23, vcc, 0, v53, vcc
	s_waitcnt vmcnt(0)
	v_lshlrev_b32_e32 v16, 16, v20
	s_nop 5
	v_pk_mul_f32 v[0:1], v[0:1], v[50:51] op_sel_hi:[1,0]
	v_pk_mul_f32 v[2:3], v[2:3], v[50:51] op_sel_hi:[1,0]
	v_and_b32_e32 v17, 0xffff0000, v20
	v_lshlrev_b32_e32 v18, 16, v21
	v_and_b32_e32 v19, 0xffff0000, v21
	v_pk_mul_f32 v[0:1], v[0:1], v[16:17]
	v_pk_mul_f32 v[2:3], v[2:3], v[18:19]
	v_cvt_pk_bf16_f32 v0, v0, v1
	v_cvt_pk_bf16_f32 v1, v2, v3
	global_store_dwordx2 v[22:23], v[0:1], off
	global_load_dwordx2 v[0:1], v[48:49], off offset:80
	v_pk_mul_f32 v[2:3], v[4:5], v[50:51] op_sel_hi:[1,0]
	v_pk_mul_f32 v[4:5], v[6:7], v[50:51] op_sel_hi:[1,0]
	s_waitcnt vmcnt(0)
	v_lshlrev_b32_e32 v6, 16, v0
	v_and_b32_e32 v7, 0xffff0000, v0
	v_lshlrev_b32_e32 v0, 16, v1
	v_and_b32_e32 v1, 0xffff0000, v1
	v_pk_mul_f32 v[2:3], v[2:3], v[6:7]
	v_pk_mul_f32 v[0:1], v[4:5], v[0:1]
	v_cvt_pk_bf16_f32 v2, v2, v3
	v_cvt_pk_bf16_f32 v3, v0, v1
	global_store_dwordx2 v[22:23], v[2:3], off offset:16
	global_load_dwordx2 v[0:1], v[48:49], off offset:96
	v_pk_mul_f32 v[2:3], v[8:9], v[50:51] op_sel_hi:[1,0]
	v_pk_mul_f32 v[4:5], v[10:11], v[50:51] op_sel_hi:[1,0]
	s_waitcnt vmcnt(0)
	v_lshlrev_b32_e32 v6, 16, v0
	v_and_b32_e32 v7, 0xffff0000, v0
	v_lshlrev_b32_e32 v0, 16, v1
	v_and_b32_e32 v1, 0xffff0000, v1
	v_pk_mul_f32 v[2:3], v[2:3], v[6:7]
	v_pk_mul_f32 v[0:1], v[4:5], v[0:1]
	v_cvt_pk_bf16_f32 v2, v2, v3
	v_cvt_pk_bf16_f32 v3, v0, v1
	global_store_dwordx2 v[22:23], v[2:3], off offset:32
	global_load_dwordx2 v[0:1], v[48:49], off offset:112
	v_pk_mul_f32 v[2:3], v[12:13], v[50:51] op_sel_hi:[1,0]
	v_pk_mul_f32 v[4:5], v[14:15], v[50:51] op_sel_hi:[1,0]
	s_waitcnt vmcnt(0)
	v_lshlrev_b32_e32 v6, 16, v0
	v_and_b32_e32 v7, 0xffff0000, v0
	v_lshlrev_b32_e32 v0, 16, v1
	v_and_b32_e32 v1, 0xffff0000, v1
	v_pk_mul_f32 v[2:3], v[2:3], v[6:7]
	v_pk_mul_f32 v[0:1], v[4:5], v[0:1]
	v_cvt_pk_bf16_f32 v2, v2, v3
	v_cvt_pk_bf16_f32 v3, v0, v1
	global_store_dwordx2 v[22:23], v[2:3], off offset:48
	s_branch .LBB0_85

; DI unsigned pk2(float a, float b) { f2_t v = {a, b}; bf2_t r = __builtin_convertvector(v, bf2_t); return __builtin_bit_cast(unsigned, r); }
; DI float bf2f(bf16_t v) { return __uint_as_float(((unsigned)v) << 16); }
; DI int otid() { int t = threadIdx.x; asm volatile("" : "+v"(t)); return t; }
; DI float xsum32(float x) { const unsigned u = __float_as_uint(x); const auto r2 = __builtin_amdgcn_permlane32_swap(u, u, false, false); return __uint_as_float(r2[0]) + __uint_as_float(r2[1]); }
; template <int KIND>
; DI void attn_unit(const Params& p, int l, int b, int head, int qt, int qcol, int kcol, int vfeat, int gcol, int mixcol,
;                   int t1, int n1, int t2, int n2, char* smem) {
;     ...
;     l0 = xsum32(l0);
;     const float inv0 = 1.f / l0;
;     const int tid_e = otid();
;     const size_t qrow_e = (size_t)b * TPB + qt * 128 + 32 * (tid_e >> 6) + (tid_e & 31);
;     bf16_t* orow = p.hmix + ((size_t)(mixcol >> 5) * NTOK + qrow_e) * 32;
;     const bf16_t* grow = p.qkv + ((size_t)(gcol >> 6) * NTOK + qrow_e) * 64;
;     ...
; #pragma unroll
;         for (int t = 0; t < 2; ++t)
; #pragma unroll
;             for (int q = 0; q < 4; ++q) {
;                 const int f = 32 * t + 8 * q + 4 * h;
;                 const uint2 gg = *(const uint2*)(grow + f);
;                 const float g0 = bf2f((bf16_t)(gg.x & 0xffff)), g1 = bf2f((bf16_t)(gg.x >> 16)), g2 = bf2f((bf16_t)(gg.y & 0xffff)), g3 = bf2f((bf16_t)(gg.y >> 16));
;                 uint2 o;
;                 o.x = pk2(O0[t][4 * q + 0] * inv0 * g0, O0[t][4 * q + 1] * inv0 * g1);
;                 o.y = pk2(O0[t][4 * q + 2] * inv0 * g2, O0[t][4 * q + 3] * inv0 * g3);
;                 *(uint2*)(orow + (size_t)t * NTOK * 32 + 8 * q + 4 * h) = o;
;             }
;     }
; }
; template <int Q>
; DI void attn_queue(const Params& p, int l, char* smem, int* s_unit, int cb) {
;     const bool ctxu = l < DEPTH - 1;
;     const int total = (Q == 0) ? (ctxu ? 576 : 512) : (Q == 1) ? (ctxu ? 960 : 768) : 768;
;     for (;;) {
;         if (threadIdx.x == 0) *s_unit = (int)atomicAdd(p.ctr + cb + l * 4 + Q, 1u);
.LBB0_107:
	s_mov_b64 exec, s[54:55]
	s_load_dwordx2 s[100:101], s[0:1], 0x100
	s_lshl_b32 m0, s48, 2
	v_mov_b32_e32 v253, 1
	s_waitcnt lgkmcnt(0)
	s_add_u32 s100, s100, m0
	s_addc_u32 s101, s101, 0
	global_atomic_add v253, v193, v253, s[100:101] offset:8 sc0
	s_mov_b64 exec, -1
	s_add_i32 s4, s35, 0xc80
	s_addk_i32 s35, 0x280
	v_mov_b32_e32 v34, v200
	s_add_u32 s5, s34, s28
	v_ashrrev_i32_e32 v32, 1, v34
	s_addc_u32 s6, s29, 0
	v_and_b32_e32 v32, 0xffffffe0, v32
	v_ashrrev_i32_e32 v33, 31, v32
	v_and_or_b32 v34, v34, 31, s5
	v_mov_b32_e32 v35, s6
	s_lshr_b32 s4, s4, 6
	v_lshl_add_u64 v[32:33], v[34:35], 0, v[32:33]
	s_mulk_i32 s4, 0x4800
	s_mov_b32 s5, s75
	v_lshl_add_u64 v[34:35], v[32:33], 0, s[4:5]
	v_lshlrev_b64 v[34:35], 7, v[34:35]
	v_lshl_add_u64 v[34:35], s[44:45], 0, v[34:35]
	v_lshlrev_b32_e32 v192, 1, v164
	v_lshl_add_u64 v[34:35], v[34:35], 0, v[192:193]
	global_load_dwordx2 v[36:37], v[34:35], off
	v_mov_b32_e32 v38, v179
	s_nop 1
	v_permlane32_swap_b32_e32 v179, v38
	v_add_f32_e32 v38, v179, v38
	v_div_scale_f32 v39, s[8:9], v38, v38, 1.0
	v_rcp_f32_e32 v41, v39
	v_div_scale_f32 v40, vcc, 1.0, v38, 1.0
	s_load_dwordx2 s[6:7], s[0:1], 0xb8
	v_fma_f32 v42, -v39, v41, 1.0
	v_fmac_f32_e32 v41, v42, v41
	v_mul_f32_e32 v42, v40, v41
	v_fma_f32 v43, -v39, v42, v40
	v_fmac_f32_e32 v42, v43, v41
	s_lshr_b32 s4, s35, 5
	v_fma_f32 v39, -v39, v42, v40
	s_mulk_i32 s4, 0x4800
	v_div_fmas_f32 v39, v39, v41, v42
	v_lshl_add_u64 v[32:33], v[32:33], 0, s[4:5]
	v_div_fixup_f32 v38, v39, v38, 1.0
	v_lshlrev_b64 v[32:33], 6, v[32:33]
	v_pk_mul_f32 v[16:17], v[16:17], v[38:39] op_sel_hi:[1,0]
	v_pk_mul_f32 v[18:19], v[18:19], v[38:39] op_sel_hi:[1,0]
	s_waitcnt lgkmcnt(0)
	v_lshl_add_u64 v[32:33], s[6:7], 0, v[32:33]
	v_lshl_add_u64 v[32:33], v[32:33], 0, v[192:193]
	s_mov_b32 s4, 0x120000
	v_pk_mul_f32 v[0:1], v[0:1], v[38:39] op_sel_hi:[1,0]
	v_pk_mul_f32 v[2:3], v[2:3], v[38:39] op_sel_hi:[1,0]
	s_waitcnt vmcnt(0)
	v_lshlrev_b32_e32 v40, 16, v36
	v_and_b32_e32 v41, 0xffff0000, v36
	v_lshlrev_b32_e32 v36, 16, v37
	v_and_b32_e32 v37, 0xffff0000, v37
	v_pk_mul_f32 v[16:17], v[16:17], v[40:41]
	v_pk_mul_f32 v[18:19], v[18:19], v[36:37]
	v_cvt_pk_bf16_f32 v16, v16, v17
	v_cvt_pk_bf16_f32 v17, v18, v19
	global_store_dwordx2 v[32:33], v[16:17], off
	global_load_dwordx2 v[16:17], v[34:35], off offset:16
	v_pk_mul_f32 v[18:19], v[20:21], v[38:39] op_sel_hi:[1,0]
	v_pk_mul_f32 v[20:21], v[22:23], v[38:39] op_sel_hi:[1,0]
	s_waitcnt vmcnt(0)
	v_lshlrev_b32_e32 v22, 16, v16
	v_and_b32_e32 v23, 0xffff0000, v16
	v_lshlrev_b32_e32 v16, 16, v17
	v_and_b32_e32 v17, 0xffff0000, v17
	v_pk_mul_f32 v[18:19], v[18:19], v[22:23]
	v_pk_mul_f32 v[16:17], v[20:21], v[16:17]
	v_cvt_pk_bf16_f32 v18, v18, v19
	v_cvt_pk_bf16_f32 v19, v16, v17
	global_store_dwordx2 v[32:33], v[18:19], off offset:16
	global_load_dwordx2 v[16:17], v[34:35], off offset:32
	v_pk_mul_f32 v[18:19], v[24:25], v[38:39] op_sel_hi:[1,0]
	v_pk_mul_f32 v[20:21], v[26:27], v[38:39] op_sel_hi:[1,0]
	s_waitcnt vmcnt(0)
	v_lshlrev_b32_e32 v22, 16, v16
	v_and_b32_e32 v23, 0xffff0000, v16
	v_lshlrev_b32_e32 v16, 16, v17
	v_and_b32_e32 v17, 0xffff0000, v17
	v_pk_mul_f32 v[18:19], v[18:19], v[22:23]
	v_pk_mul_f32 v[16:17], v[20:21], v[16:17]
	v_cvt_pk_bf16_f32 v18, v18, v19
	v_cvt_pk_bf16_f32 v19, v16, v17
	global_store_dwordx2 v[32:33], v[18:19], off offset:32
	global_load_dwordx2 v[16:17], v[34:35], off offset:48
	v_pk_mul_f32 v[18:19], v[28:29], v[38:39] op_sel_hi:[1,0]
	v_pk_mul_f32 v[20:21], v[30:31], v[38:39] op_sel_hi:[1,0]
	s_waitcnt vmcnt(0)
	v_lshlrev_b32_e32 v22, 16, v16
	v_and_b32_e32 v23, 0xffff0000, v16
	v_lshlrev_b32_e32 v16, 16, v17
	v_and_b32_e32 v17, 0xffff0000, v17
	v_pk_mul_f32 v[18:19], v[18:19], v[22:23]
	v_pk_mul_f32 v[16:17], v[20:21], v[16:17]
	v_cvt_pk_bf16_f32 v18, v18, v19
	v_cvt_pk_bf16_f32 v19, v16, v17
	global_store_dwordx2 v[32:33], v[18:19], off offset:48
	global_load_dwordx2 v[16:17], v[34:35], off offset:64
	v_add_co_u32_e32 v18, vcc, s4, v32
	s_mov_b64 s[4:5], 0
	s_nop 0
	v_addc_co_u32_e32 v19, vcc, 0, v33, vcc
	s_waitcnt vmcnt(0)
	v_lshlrev_b32_e32 v20, 16, v16
	v_and_b32_e32 v21, 0xffff0000, v16
	v_lshlrev_b32_e32 v16, 16, v17
	v_and_b32_e32 v17, 0xffff0000, v17
	v_pk_mul_f32 v[0:1], v[0:1], v[20:21]
	v_pk_mul_f32 v[2:3], v[2:3], v[16:17]
	v_cvt_pk_bf16_f32 v0, v0, v1
	v_cvt_pk_bf16_f32 v1, v2, v3
	global_store_dwordx2 v[18:19], v[0:1], off
	global_load_dwordx2 v[0:1], v[34:35], off offset:80
	v_pk_mul_f32 v[2:3], v[4:5], v[38:39] op_sel_hi:[1,0]
	v_pk_mul_f32 v[4:5], v[6:7], v[38:39] op_sel_hi:[1,0]
	s_waitcnt vmcnt(0)
	v_lshlrev_b32_e32 v6, 16, v0
	v_and_b32_e32 v7, 0xffff0000, v0
	v_lshlrev_b32_e32 v0, 16, v1
	v_and_b32_e32 v1, 0xffff0000, v1
	v_pk_mul_f32 v[2:3], v[2:3], v[6:7]
	v_pk_mul_f32 v[0:1], v[4:5], v[0:1]
	v_cvt_pk_bf16_f32 v2, v2, v3
	v_cvt_pk_bf16_f32 v3, v0, v1
	global_store_dwordx2 v[18:19], v[2:3], off offset:16
	global_load_dwordx2 v[0:1], v[34:35], off offset:96
	v_pk_mul_f32 v[2:3], v[8:9], v[38:39] op_sel_hi:[1,0]
	v_pk_mul_f32 v[4:5], v[10:11], v[38:39] op_sel_hi:[1,0]
	s_waitcnt vmcnt(0)
	v_lshlrev_b32_e32 v6, 16, v0
	v_and_b32_e32 v7, 0xffff0000, v0
	v_lshlrev_b32_e32 v0, 16, v1
	v_and_b32_e32 v1, 0xffff0000, v1
	v_pk_mul_f32 v[2:3], v[2:3], v[6:7]
	v_pk_mul_f32 v[0:1], v[4:5], v[0:1]
	v_cvt_pk_bf16_f32 v2, v2, v3
	v_cvt_pk_bf16_f32 v3, v0, v1
	global_store_dwordx2 v[18:19], v[2:3], off offset:32
	global_load_dwordx2 v[0:1], v[34:35], off offset:112
	v_pk_mul_f32 v[2:3], v[12:13], v[38:39] op_sel_hi:[1,0]
	v_pk_mul_f32 v[4:5], v[14:15], v[38:39] op_sel_hi:[1,0]
	s_waitcnt vmcnt(0)
	v_lshlrev_b32_e32 v6, 16, v0
	v_and_b32_e32 v7, 0xffff0000, v0
	v_lshlrev_b32_e32 v0, 16, v1
	v_and_b32_e32 v1, 0xffff0000, v1
	v_pk_mul_f32 v[2:3], v[2:3], v[6:7]
	v_pk_mul_f32 v[0:1], v[4:5], v[0:1]
	v_cvt_pk_bf16_f32 v2, v2, v3
	v_cvt_pk_bf16_f32 v3, v0, v1
	global_store_dwordx2 v[18:19], v[2:3], off offset:48
